# plus P GEMM LDS-DMA in SGPR-base form (no 64-bit VALU address adds in load segments)
# baseline (speedup 1.0000x reference)
; #define PG8_STAGE(bufoff, gbase, voff) do { _Pragma("unroll") for (int _i = 0; _i < 2; ++_i) \
;         __builtin_amdgcn_global_load_lds((const unsigned*)((const char*)(gbase) + (voff)[_i]), (PG8_LAS unsigned*)(lds + (bufoff) + ldsw + _i * 8192), 16, 0, 0); } while (0)
; #define PG8_LDA(dst, b, h) do { _Pragma("unroll") for (int m = 0; m < 4; ++m) _Pragma("unroll") for (int k = 0; k < 2; ++k) dst[m][k] = *(const PG8_LAS bf16x8*)(lds + PG8_SA(b, h) + aoff + m * 2048 + k * 1024); } while (0)
; #define PG8_LDB(dst, b, h) do { _Pragma("unroll") for (int n = 0; n < 2; ++n) _Pragma("unroll") for (int k = 0; k < 2; ++k) dst[n][k] = *(const PG8_LAS bf16x8*)(lds + PG8_SB(b, h) + boff + n * 2048 + k * 1024); } while (0)
; #define PG8_MMA(ai, bj, At, Bt) do { __builtin_amdgcn_s_setprio(1); _Pragma("unroll") for (int m = 0; m < 4; ++m) _Pragma("unroll") for (int n = 0; n < 2; ++n) _Pragma("unroll") for (int k = 0; k < 2; ++k) \
;         acc[ai][bj][m][n] = __builtin_amdgcn_mfma_f32_16x16x32_bf16(Bt[n][k], At[m][k], acc[ai][bj][m][n], 0, 0, 0); __builtin_amdgcn_s_setprio(0); } while (0)
; #define PG8_WAIT_V(n) asm volatile("s_waitcnt vmcnt(" #n ")" ::: "memory")
; #define PG8_BAR __builtin_amdgcn_s_barrier()
; template <class Epi, class Sched, bool ALIGN_EPI = false, bool SP2 = false>
; __device__ __forceinline__ void gemm_phase(PG8_LAS unsigned char* lds, const Gemm g, const Sched& S, const Epi& E) {
;     ...
;         for (int t = 0; t < nt; t += 2) {
;             const bool last = (t == nt - 2);
;             const char* a1 = cA + (size_t)(t + 1) * kstep;
;             const char* a2 = last ? nA : cA + (size_t)(t + 2) * kstep; const char* b2 = last ? nB : cB + (size_t)(t + 2) * kstep;
;             const char* a3 = a2 + kstep; const char* b3 = b2 + kstep;
;             if (last && has_next) S.a_ready(nxt);
;             if constexpr (SP2) {
;             PG8_LDB(B0, 0, 0); PG8_LDB(B1, 0, 1); PG8_SCHED; PG8_LDA(At, 0, 0); PG8_STAGE(PG8_SA(1, 1), a1 + hstep, voffA);
;             PG8_WAIT_V(8); PG8_WAIT_L(0); PG8_BAR; PG8_MMA(0, 0, At, B0); PG8_MMA(0, 1, At, B1); PG8_BAR; PG8_SCHED;
;             PG8_LDA(At, 0, 1); PG8_STAGE(PG8_SB(0, 0), b2, voffB); PG8_STAGE(PG8_SB(0, 1), b2 + hstep, voffB); PG8_STAGE(PG8_SA(0, 0), a2, voffA);
;             PG8_WAIT_V(8); PG8_WAIT_L(0); PG8_BAR; PG8_MMA(1, 0, At, B0); PG8_MMA(1, 1, At, B1); PG8_BAR; PG8_SCHED;
.LBB0_170:
	s_sub_i32 vcc_hi, 0x29000, s100
	s_sub_i32 vcc_hi, vcc_hi, s101
	s_add_u32 s26, s38, 0xfff80080
	s_addc_u32 s27, s39, -1
	s_add_i32 s50, 0, 0x10000
	s_cmp_eq_u32 s49, 28
	s_cselect_b32 s41, s7, s27
	s_cselect_b32 s40, s19, s26
	s_cselect_b32 s27, s17, s48
	s_cselect_b32 s26, s46, s47
	s_add_i32 s52, 0, 0x14000
	v_add_u32_e32 v156, s50, v145
	v_add_u32_e32 v172, s52, v145
	ds_read_b128 v[140:143], v156
	ds_read_b128 v[148:151], v156 offset:1024
	ds_read_b128 v[152:155], v156 offset:2048
	ds_read_b128 v[156:159], v156 offset:3072
	ds_read_b128 v[160:163], v172
	ds_read_b128 v[164:167], v172 offset:1024
	ds_read_b128 v[168:171], v172 offset:2048
	ds_read_b128 v[172:175], v172 offset:3072
	s_add_i32 m0, s25, 0xc000
	v_add_u32_e32 v250, s100, v147
	ds_read_b128 v[176:179], v250
	ds_read_b128 v[180:183], v250 offset:1024
	ds_read_b128 v[184:187], v250 offset:2048
	ds_read_b128 v[188:191], v250 offset:3072
	ds_read_b128 v[192:195], v250 offset:4096
	ds_read_b128 v[202:205], v250 offset:5120
	ds_read_b128 v[206:209], v250 offset:6144
	ds_read_b128 v[210:213], v250 offset:7168
	global_load_lds_dwordx4 v136, s[38:39]
	s_add_i32 m0, s25, 0xe000
	s_nop 0
	global_load_lds_dwordx4 v138, s[38:39]
	s_add_i32 m0, vcc_hi, s25
	s_nop 0
	global_load_lds_dwordx4 v130, s[40:41]
	s_add_i32 m0, m0, 0x2000
	s_nop 0
	global_load_lds_dwordx4 v132, s[40:41]
	s_waitcnt vmcnt(10)
	s_waitcnt lgkmcnt(0)
	s_setprio 1
	s_waitcnt lgkmcnt(0)
	v_mfma_f32_16x16x32_bf16 v[122:125], v[140:143], v[176:179], v[122:125]
	v_mfma_f32_16x16x32_bf16 v[126:129], v[152:155], v[176:179], v[126:129]
	v_mfma_f32_16x16x32_bf16 v[106:109], v[140:143], v[184:187], v[106:109]
	v_mfma_f32_16x16x32_bf16 v[110:113], v[152:155], v[184:187], v[110:113]
	s_barrier
	v_mfma_f32_16x16x32_bf16 v[90:93], v[140:143], v[192:195], v[90:93]
	v_mfma_f32_16x16x32_bf16 v[94:97], v[152:155], v[192:195], v[94:97]
	v_mfma_f32_16x16x32_bf16 v[74:77], v[140:143], v[206:209], v[74:77]
	v_mfma_f32_16x16x32_bf16 v[78:81], v[152:155], v[206:209], v[78:81]
	v_mfma_f32_16x16x32_bf16 v[122:125], v[148:151], v[180:183], v[122:125]
	v_mfma_f32_16x16x32_bf16 v[126:129], v[156:159], v[180:183], v[126:129]
	v_mfma_f32_16x16x32_bf16 v[106:109], v[148:151], v[188:191], v[106:109]
	v_mfma_f32_16x16x32_bf16 v[110:113], v[156:159], v[188:191], v[110:113]
	v_mfma_f32_16x16x32_bf16 v[90:93], v[148:151], v[202:205], v[90:93]
	v_mfma_f32_16x16x32_bf16 v[94:97], v[156:159], v[202:205], v[94:97]
	v_mfma_f32_16x16x32_bf16 v[74:77], v[148:151], v[210:213], v[74:77]
	v_mfma_f32_16x16x32_bf16 v[78:81], v[156:159], v[210:213], v[78:81]
	s_setprio 0
	s_setprio 1
	v_mfma_f32_16x16x32_bf16 v[114:117], v[160:163], v[176:179], v[114:117]
	v_mfma_f32_16x16x32_bf16 v[118:121], v[168:171], v[176:179], v[118:121]
	v_mfma_f32_16x16x32_bf16 v[98:101], v[160:163], v[184:187], v[98:101]
	v_mfma_f32_16x16x32_bf16 v[102:105], v[168:171], v[184:187], v[102:105]
	v_mfma_f32_16x16x32_bf16 v[82:85], v[160:163], v[192:195], v[82:85]
	v_mfma_f32_16x16x32_bf16 v[86:89], v[168:171], v[192:195], v[86:89]
	v_mfma_f32_16x16x32_bf16 v[66:69], v[160:163], v[206:209], v[66:69]
	v_mfma_f32_16x16x32_bf16 v[70:73], v[168:171], v[206:209], v[70:73]
	v_mfma_f32_16x16x32_bf16 v[114:117], v[164:167], v[180:183], v[114:117]
	v_mfma_f32_16x16x32_bf16 v[118:121], v[172:175], v[180:183], v[118:121]
	v_mfma_f32_16x16x32_bf16 v[98:101], v[164:167], v[188:191], v[98:101]
	v_mfma_f32_16x16x32_bf16 v[102:105], v[172:175], v[188:191], v[102:105]
	v_mfma_f32_16x16x32_bf16 v[82:85], v[164:167], v[202:205], v[82:85]
	v_mfma_f32_16x16x32_bf16 v[86:89], v[172:175], v[202:205], v[86:89]
	v_mfma_f32_16x16x32_bf16 v[66:69], v[164:167], v[210:213], v[66:69]
	v_mfma_f32_16x16x32_bf16 v[70:73], v[172:175], v[210:213], v[70:73]
	s_setprio 0
	s_barrier
	s_add_i32 s50, s50, s29
	s_mov_b32 m0, s50
	ds_read_b128 v[176:179], v147 offset:16384
	ds_read_b128 v[180:183], v147 offset:17408
	ds_read_b128 v[184:187], v147 offset:18432
	ds_read_b128 v[188:191], v147 offset:19456
	ds_read_b128 v[192:195], v147 offset:20480
	ds_read_b128 v[202:205], v147 offset:21504
	ds_read_b128 v[206:209], v147 offset:22528
	ds_read_b128 v[210:213], v147 offset:23552
	global_load_lds_dwordx4 v0, s[26:27]
	s_add_i32 m0, s50, 0x2000
	s_add_u32 s50, s26, 0x80000
	s_addc_u32 s51, s27, 0
	s_add_i32 s52, s52, s29
	global_load_lds_dwordx4 v134, s[26:27]
	s_mov_b32 m0, s52
	s_nop 0
	global_load_lds_dwordx4 v0, s[50:51]
	s_add_i32 m0, s52, 0x2000
	s_nop 0
	global_load_lds_dwordx4 v134, s[50:51]
	s_waitcnt vmcnt(8)
	s_waitcnt lgkmcnt(0)
	s_setprio 1
	s_waitcnt lgkmcnt(0)
	v_mfma_f32_16x16x32_bf16 v[58:61], v[140:143], v[176:179], v[58:61]
	v_mfma_f32_16x16x32_bf16 v[62:65], v[152:155], v[176:179], v[62:65]
	v_mfma_f32_16x16x32_bf16 v[42:45], v[140:143], v[184:187], v[42:45]
	v_mfma_f32_16x16x32_bf16 v[46:49], v[152:155], v[184:187], v[46:49]
	s_barrier
; #define PG8_STAGE(bufoff, gbase, voff) do { _Pragma("unroll") for (int _i = 0; _i < 2; ++_i) \
;         __builtin_amdgcn_global_load_lds((const unsigned*)((const char*)(gbase) + (voff)[_i]), (PG8_LAS unsigned*)(lds + (bufoff) + ldsw + _i * 8192), 16, 0, 0); } while (0)
; #define PG8_LDA(dst, b, h) do { _Pragma("unroll") for (int m = 0; m < 4; ++m) _Pragma("unroll") for (int k = 0; k < 2; ++k) dst[m][k] = *(const PG8_LAS bf16x8*)(lds + PG8_SA(b, h) + aoff + m * 2048 + k * 1024); } while (0)
; #define PG8_LDB(dst, b, h) do { _Pragma("unroll") for (int n = 0; n < 2; ++n) _Pragma("unroll") for (int k = 0; k < 2; ++k) dst[n][k] = *(const PG8_LAS bf16x8*)(lds + PG8_SB(b, h) + boff + n * 2048 + k * 1024); } while (0)
; #define PG8_MMA(ai, bj, At, Bt) do { __builtin_amdgcn_s_setprio(1); _Pragma("unroll") for (int m = 0; m < 4; ++m) _Pragma("unroll") for (int n = 0; n < 2; ++n) _Pragma("unroll") for (int k = 0; k < 2; ++k) \
;         acc[ai][bj][m][n] = __builtin_amdgcn_mfma_f32_16x16x32_bf16(Bt[n][k], At[m][k], acc[ai][bj][m][n], 0, 0, 0); __builtin_amdgcn_s_setprio(0); } while (0)
; #define PG8_WAIT_V(n) asm volatile("s_waitcnt vmcnt(" #n ")" ::: "memory")
; #define PG8_WAIT_L(n) asm volatile("s_waitcnt lgkmcnt(" #n ")" ::: "memory")
; #define PG8_BAR __builtin_amdgcn_s_barrier()
; #define PG8_SCHED __builtin_amdgcn_sched_barrier(0)
; template <class Epi, class Sched, bool ALIGN_EPI = false, bool SP2 = false>
; __device__ __forceinline__ void gemm_phase(PG8_LAS unsigned char* lds, const Gemm g, const Sched& S, const Epi& E) {
;     ...
;             PG8_WAIT_V(8); PG8_WAIT_L(0); PG8_BAR; PG8_MMA(0, 0, At, B0); PG8_MMA(0, 1, At, B1); PG8_BAR; PG8_SCHED;
;             PG8_LDA(At, 0, 1); PG8_STAGE(PG8_SB(0, 0), b2, voffB); PG8_STAGE(PG8_SB(0, 1), b2 + hstep, voffB); PG8_STAGE(PG8_SA(0, 0), a2, voffA);
;             PG8_WAIT_V(8); PG8_WAIT_L(0); PG8_BAR; PG8_MMA(1, 0, At, B0); PG8_MMA(1, 1, At, B1); PG8_BAR; PG8_SCHED;
;             PG8_LDB(B0, 1, 0); PG8_LDB(B1, 1, 1); PG8_SCHED; PG8_LDA(At, 1, 0); PG8_STAGE(PG8_SA(0, 1), a2 + hstep, voffA);
;             PG8_WAIT_V(8); PG8_WAIT_L(0); PG8_BAR; PG8_MMA(0, 0, At, B0); PG8_MMA(0, 1, At, B1); PG8_BAR; PG8_SCHED;
	v_mfma_f32_16x16x32_bf16 v[26:29], v[140:143], v[192:195], v[26:29]
	v_mfma_f32_16x16x32_bf16 v[30:33], v[152:155], v[192:195], v[30:33]
	v_mfma_f32_16x16x32_bf16 v[10:13], v[140:143], v[206:209], v[10:13]
	v_mfma_f32_16x16x32_bf16 v[14:17], v[152:155], v[206:209], v[14:17]
	v_mfma_f32_16x16x32_bf16 v[58:61], v[148:151], v[180:183], v[58:61]
	v_mfma_f32_16x16x32_bf16 v[62:65], v[156:159], v[180:183], v[62:65]
	v_mfma_f32_16x16x32_bf16 v[42:45], v[148:151], v[188:191], v[42:45]
	v_mfma_f32_16x16x32_bf16 v[46:49], v[156:159], v[188:191], v[46:49]
	v_mfma_f32_16x16x32_bf16 v[26:29], v[148:151], v[202:205], v[26:29]
	v_mfma_f32_16x16x32_bf16 v[30:33], v[156:159], v[202:205], v[30:33]
	v_mfma_f32_16x16x32_bf16 v[10:13], v[148:151], v[210:213], v[10:13]
	v_mfma_f32_16x16x32_bf16 v[14:17], v[156:159], v[210:213], v[14:17]
	s_setprio 0
	s_setprio 1
	v_mfma_f32_16x16x32_bf16 v[50:53], v[160:163], v[176:179], v[50:53]
	v_mfma_f32_16x16x32_bf16 v[54:57], v[168:171], v[176:179], v[54:57]
	v_mfma_f32_16x16x32_bf16 v[34:37], v[160:163], v[184:187], v[34:37]
	v_mfma_f32_16x16x32_bf16 v[38:41], v[168:171], v[184:187], v[38:41]
	v_mfma_f32_16x16x32_bf16 v[18:21], v[160:163], v[192:195], v[18:21]
	v_mfma_f32_16x16x32_bf16 v[22:25], v[168:171], v[192:195], v[22:25]
	v_mfma_f32_16x16x32_bf16 v[2:5], v[160:163], v[206:209], v[2:5]
	v_mfma_f32_16x16x32_bf16 v[6:9], v[168:171], v[206:209], v[6:9]
	v_mfma_f32_16x16x32_bf16 v[50:53], v[164:167], v[180:183], v[50:53]
	v_mfma_f32_16x16x32_bf16 v[54:57], v[172:175], v[180:183], v[54:57]
	v_mfma_f32_16x16x32_bf16 v[34:37], v[164:167], v[188:191], v[34:37]
	v_mfma_f32_16x16x32_bf16 v[38:41], v[172:175], v[188:191], v[38:41]
	v_mfma_f32_16x16x32_bf16 v[18:21], v[164:167], v[202:205], v[18:21]
	v_mfma_f32_16x16x32_bf16 v[22:25], v[172:175], v[202:205], v[22:25]
	v_mfma_f32_16x16x32_bf16 v[2:5], v[164:167], v[210:213], v[2:5]
	v_mfma_f32_16x16x32_bf16 v[6:9], v[172:175], v[210:213], v[6:9]
	s_setprio 0
	s_barrier
	s_add_i32 s50, 0, 0x18000
	s_add_i32 s51, 0, 0x1c000
	v_add_u32_e32 v156, s50, v145
	v_add_u32_e32 v172, s51, v145
	ds_read_b128 v[140:143], v156
	ds_read_b128 v[148:151], v156 offset:1024
	ds_read_b128 v[152:155], v156 offset:2048
	ds_read_b128 v[156:159], v156 offset:3072
	ds_read_b128 v[160:163], v172
	ds_read_b128 v[164:167], v172 offset:1024
	ds_read_b128 v[168:171], v172 offset:2048
	ds_read_b128 v[172:175], v172 offset:3072
	s_add_u32 s40, s40, 0x80000
	s_addc_u32 s41, s41, 0
	s_mov_b32 m0, s31
	v_add_u32_e32 v250, s101, v147
	ds_read_b128 v[176:179], v250
	ds_read_b128 v[180:183], v250 offset:1024
	ds_read_b128 v[184:187], v250 offset:2048
	ds_read_b128 v[188:191], v250 offset:3072
	ds_read_b128 v[192:195], v250 offset:4096
	ds_read_b128 v[202:205], v250 offset:5120
	ds_read_b128 v[206:209], v250 offset:6144
	ds_read_b128 v[210:213], v250 offset:7168
	global_load_lds_dwordx4 v130, s[40:41]
	s_mov_b32 m0, s42
	s_nop 0
	global_load_lds_dwordx4 v132, s[40:41]
	s_sub_u32 s40, s40, 0x7ff80
	s_subb_u32 s41, s41, 0
	s_add_i32 m0, s100, s25
	s_nop 0
	global_load_lds_dwordx4 v130, s[40:41]
	s_add_i32 m0, m0, 0x2000
	s_nop 0
	global_load_lds_dwordx4 v132, s[40:41]
	s_waitcnt vmcnt(10)
	s_waitcnt lgkmcnt(0)
	s_setprio 1
	s_waitcnt lgkmcnt(0)
	v_mfma_f32_16x16x32_bf16 v[122:125], v[140:143], v[176:179], v[122:125]
	v_mfma_f32_16x16x32_bf16 v[126:129], v[152:155], v[176:179], v[126:129]
	v_mfma_f32_16x16x32_bf16 v[106:109], v[140:143], v[184:187], v[106:109]
	v_mfma_f32_16x16x32_bf16 v[110:113], v[152:155], v[184:187], v[110:113]
	s_barrier
; #define PG8_STAGE(bufoff, gbase, voff) do { _Pragma("unroll") for (int _i = 0; _i < 2; ++_i) \
;         __builtin_amdgcn_global_load_lds((const unsigned*)((const char*)(gbase) + (voff)[_i]), (PG8_LAS unsigned*)(lds + (bufoff) + ldsw + _i * 8192), 16, 0, 0); } while (0)
; #define PG8_LDA(dst, b, h) do { _Pragma("unroll") for (int m = 0; m < 4; ++m) _Pragma("unroll") for (int k = 0; k < 2; ++k) dst[m][k] = *(const PG8_LAS bf16x8*)(lds + PG8_SA(b, h) + aoff + m * 2048 + k * 1024); } while (0)
; #define PG8_LDB(dst, b, h) do { _Pragma("unroll") for (int n = 0; n < 2; ++n) _Pragma("unroll") for (int k = 0; k < 2; ++k) dst[n][k] = *(const PG8_LAS bf16x8*)(lds + PG8_SB(b, h) + boff + n * 2048 + k * 1024); } while (0)
; #define PG8_MMA(ai, bj, At, Bt) do { __builtin_amdgcn_s_setprio(1); _Pragma("unroll") for (int m = 0; m < 4; ++m) _Pragma("unroll") for (int n = 0; n < 2; ++n) _Pragma("unroll") for (int k = 0; k < 2; ++k) \
;         acc[ai][bj][m][n] = __builtin_amdgcn_mfma_f32_16x16x32_bf16(Bt[n][k], At[m][k], acc[ai][bj][m][n], 0, 0, 0); __builtin_amdgcn_s_setprio(0); } while (0)
; #define PG8_WAIT_V(n) asm volatile("s_waitcnt vmcnt(" #n ")" ::: "memory")
; #define PG8_WAIT_L(n) asm volatile("s_waitcnt lgkmcnt(" #n ")" ::: "memory")
; template <class Epi, class Sched, bool ALIGN_EPI = false, bool SP2 = false>
; __device__ __forceinline__ void gemm_phase(PG8_LAS unsigned char* lds, const Gemm g, const Sched& S, const Epi& E) {
;     ...
;         for (int t = 0; t < nt; t += 2) {
;             const bool last = (t == nt - 2);
;             const char* a1 = cA + (size_t)(t + 1) * kstep;
;             const char* a2 = last ? nA : cA + (size_t)(t + 2) * kstep; const char* b2 = last ? nB : cB + (size_t)(t + 2) * kstep;
;             const char* a3 = a2 + kstep; const char* b3 = b2 + kstep;
;             if (last && has_next) S.a_ready(nxt);
;     ...
;             PG8_LDB(B0, 1, 0); PG8_LDB(B1, 1, 1); PG8_SCHED; PG8_LDA(At, 1, 0); PG8_STAGE(PG8_SA(0, 1), a2 + hstep, voffA);
;             PG8_WAIT_V(8); PG8_WAIT_L(0); PG8_BAR; PG8_MMA(0, 0, At, B0); PG8_MMA(0, 1, At, B1); PG8_BAR; PG8_SCHED;
;             PG8_LDA(At, 1, 1); PG8_STAGE(PG8_SB(1, 0), b3, voffB); PG8_STAGE(PG8_SB(1, 1), b3 + hstep, voffB); PG8_STAGE(PG8_SA(1, 0), a3, voffA);
;             PG8_WAIT_V(8); PG8_WAIT_L(0); PG8_BAR; PG8_MMA(1, 0, At, B0); PG8_MMA(1, 1, At, B1); PG8_BAR; PG8_SCHED;
	v_mfma_f32_16x16x32_bf16 v[90:93], v[140:143], v[192:195], v[90:93]
	v_mfma_f32_16x16x32_bf16 v[94:97], v[152:155], v[192:195], v[94:97]
	v_mfma_f32_16x16x32_bf16 v[74:77], v[140:143], v[206:209], v[74:77]
	v_mfma_f32_16x16x32_bf16 v[78:81], v[152:155], v[206:209], v[78:81]
	v_mfma_f32_16x16x32_bf16 v[122:125], v[148:151], v[180:183], v[122:125]
	v_mfma_f32_16x16x32_bf16 v[126:129], v[156:159], v[180:183], v[126:129]
	v_mfma_f32_16x16x32_bf16 v[106:109], v[148:151], v[188:191], v[106:109]
	v_mfma_f32_16x16x32_bf16 v[110:113], v[156:159], v[188:191], v[110:113]
	v_mfma_f32_16x16x32_bf16 v[90:93], v[148:151], v[202:205], v[90:93]
	v_mfma_f32_16x16x32_bf16 v[94:97], v[156:159], v[202:205], v[94:97]
	v_mfma_f32_16x16x32_bf16 v[74:77], v[148:151], v[210:213], v[74:77]
	v_mfma_f32_16x16x32_bf16 v[78:81], v[156:159], v[210:213], v[78:81]
	s_setprio 0
	s_setprio 1
	v_mfma_f32_16x16x32_bf16 v[114:117], v[160:163], v[176:179], v[114:117]
	v_mfma_f32_16x16x32_bf16 v[118:121], v[168:171], v[176:179], v[118:121]
	v_mfma_f32_16x16x32_bf16 v[98:101], v[160:163], v[184:187], v[98:101]
	v_mfma_f32_16x16x32_bf16 v[102:105], v[168:171], v[184:187], v[102:105]
	v_mfma_f32_16x16x32_bf16 v[82:85], v[160:163], v[192:195], v[82:85]
	v_mfma_f32_16x16x32_bf16 v[86:89], v[168:171], v[192:195], v[86:89]
	v_mfma_f32_16x16x32_bf16 v[66:69], v[160:163], v[206:209], v[66:69]
	v_mfma_f32_16x16x32_bf16 v[70:73], v[168:171], v[206:209], v[70:73]
	v_mfma_f32_16x16x32_bf16 v[114:117], v[164:167], v[180:183], v[114:117]
	v_mfma_f32_16x16x32_bf16 v[118:121], v[172:175], v[180:183], v[118:121]
	v_mfma_f32_16x16x32_bf16 v[98:101], v[164:167], v[188:191], v[98:101]
	v_mfma_f32_16x16x32_bf16 v[102:105], v[172:175], v[188:191], v[102:105]
	v_mfma_f32_16x16x32_bf16 v[82:85], v[164:167], v[202:205], v[82:85]
	v_mfma_f32_16x16x32_bf16 v[86:89], v[172:175], v[202:205], v[86:89]
	v_mfma_f32_16x16x32_bf16 v[66:69], v[164:167], v[210:213], v[66:69]
	v_mfma_f32_16x16x32_bf16 v[70:73], v[172:175], v[210:213], v[70:73]
	s_setprio 0
	s_barrier
	s_add_i32 s40, s50, s29
	s_mov_b32 m0, s40
	ds_read_b128 v[176:179], v147 offset:49152
	ds_read_b128 v[180:183], v147 offset:50176
	ds_read_b128 v[184:187], v147 offset:51200
	ds_read_b128 v[188:191], v147 offset:52224
	ds_read_b128 v[192:195], v147 offset:53248
	ds_read_b128 v[202:205], v147 offset:54272
	ds_read_b128 v[206:209], v147 offset:55296
	ds_read_b128 v[210:213], v147 offset:56320
	s_add_u32 s26, s26, 0x80
	s_addc_u32 s27, s27, 0
	global_load_lds_dwordx4 v0, s[26:27]
	s_add_i32 m0, s40, 0x2000
	s_add_i32 s40, s51, s29
	global_load_lds_dwordx4 v134, s[26:27]
	s_add_u32 s26, s26, 0x80000
	s_addc_u32 s27, s27, 0
	s_mov_b32 m0, s40
	s_nop 0
	global_load_lds_dwordx4 v0, s[26:27]
	s_add_i32 m0, s40, 0x2000
	s_nop 0
	global_load_lds_dwordx4 v134, s[26:27]
	s_waitcnt vmcnt(8)
	s_waitcnt lgkmcnt(0)
	s_setprio 1
	s_waitcnt lgkmcnt(0)
	v_mfma_f32_16x16x32_bf16 v[58:61], v[140:143], v[176:179], v[58:61]
	v_mfma_f32_16x16x32_bf16 v[62:65], v[152:155], v[176:179], v[62:65]
	v_mfma_f32_16x16x32_bf16 v[42:45], v[140:143], v[184:187], v[42:45]
	v_mfma_f32_16x16x32_bf16 v[46:49], v[152:155], v[184:187], v[46:49]
	s_barrier
	v_mfma_f32_16x16x32_bf16 v[26:29], v[140:143], v[192:195], v[26:29]
	v_mfma_f32_16x16x32_bf16 v[30:33], v[152:155], v[192:195], v[30:33]
	v_mfma_f32_16x16x32_bf16 v[10:13], v[140:143], v[206:209], v[10:13]
	v_mfma_f32_16x16x32_bf16 v[14:17], v[152:155], v[206:209], v[14:17]
	v_mfma_f32_16x16x32_bf16 v[58:61], v[148:151], v[180:183], v[58:61]
	v_mfma_f32_16x16x32_bf16 v[62:65], v[156:159], v[180:183], v[62:65]
	v_mfma_f32_16x16x32_bf16 v[42:45], v[148:151], v[188:191], v[42:45]
	v_mfma_f32_16x16x32_bf16 v[46:49], v[156:159], v[188:191], v[46:49]
	v_mfma_f32_16x16x32_bf16 v[26:29], v[148:151], v[202:205], v[26:29]
	v_mfma_f32_16x16x32_bf16 v[30:33], v[156:159], v[202:205], v[30:33]
	v_mfma_f32_16x16x32_bf16 v[10:13], v[148:151], v[210:213], v[10:13]
	v_mfma_f32_16x16x32_bf16 v[14:17], v[156:159], v[210:213], v[14:17]
	s_setprio 0
	s_setprio 1
	v_mfma_f32_16x16x32_bf16 v[50:53], v[160:163], v[176:179], v[50:53]
	v_mfma_f32_16x16x32_bf16 v[54:57], v[168:171], v[176:179], v[54:57]
	v_mfma_f32_16x16x32_bf16 v[34:37], v[160:163], v[184:187], v[34:37]
	v_mfma_f32_16x16x32_bf16 v[38:41], v[168:171], v[184:187], v[38:41]
	v_mfma_f32_16x16x32_bf16 v[18:21], v[160:163], v[192:195], v[18:21]
	v_mfma_f32_16x16x32_bf16 v[22:25], v[168:171], v[192:195], v[22:25]
	v_mfma_f32_16x16x32_bf16 v[2:5], v[160:163], v[206:209], v[2:5]
	v_mfma_f32_16x16x32_bf16 v[6:9], v[168:171], v[206:209], v[6:9]
	v_mfma_f32_16x16x32_bf16 v[50:53], v[164:167], v[180:183], v[50:53]
	v_mfma_f32_16x16x32_bf16 v[54:57], v[172:175], v[180:183], v[54:57]
	v_mfma_f32_16x16x32_bf16 v[34:37], v[164:167], v[188:191], v[34:37]
	v_mfma_f32_16x16x32_bf16 v[38:41], v[172:175], v[188:191], v[38:41]
	v_mfma_f32_16x16x32_bf16 v[18:21], v[164:167], v[202:205], v[18:21]
	v_mfma_f32_16x16x32_bf16 v[22:25], v[172:175], v[202:205], v[22:25]
	v_mfma_f32_16x16x32_bf16 v[2:5], v[164:167], v[210:213], v[2:5]
	v_mfma_f32_16x16x32_bf16 v[6:9], v[172:175], v[210:213], v[6:9]
	s_setprio 0
	s_barrier
	s_add_i32 s49, s49, 2
	s_mov_b32 s101, s100
	s_mov_b32 s100, vcc_hi
	s_add_u32 s38, s38, 0x100
	s_addc_u32 s39, s39, 0
	s_add_u32 s47, s47, 0x100
	s_addc_u32 s48, s48, 0
	s_cmp_gt_u32 s49, 29
	s_cbranch_scc0 .LBB0_170
	s_and_b64 vcc, exec, s[14:15]
	s_cbranch_vccz .LBB0_173
	s_barrier

; #define PG8_STAGE(bufoff, gbase, voff) do { _Pragma("unroll") for (int _i = 0; _i < 2; ++_i) \
;         __builtin_amdgcn_global_load_lds((const unsigned*)((const char*)(gbase) + (voff)[_i]), (PG8_LAS unsigned*)(lds + (bufoff) + ldsw + _i * 8192), 16, 0, 0); } while (0)
; #define PG8_LDA(dst, b, h) do { _Pragma("unroll") for (int m = 0; m < 4; ++m) _Pragma("unroll") for (int k = 0; k < 2; ++k) dst[m][k] = *(const PG8_LAS bf16x8*)(lds + PG8_SA(b, h) + aoff + m * 2048 + k * 1024); } while (0)
; #define PG8_LDB(dst, b, h) do { _Pragma("unroll") for (int n = 0; n < 2; ++n) _Pragma("unroll") for (int k = 0; k < 2; ++k) dst[n][k] = *(const PG8_LAS bf16x8*)(lds + PG8_SB(b, h) + boff + n * 2048 + k * 1024); } while (0)
; #define PG8_MMA(ai, bj, At, Bt) do { __builtin_amdgcn_s_setprio(1); _Pragma("unroll") for (int m = 0; m < 4; ++m) _Pragma("unroll") for (int n = 0; n < 2; ++n) _Pragma("unroll") for (int k = 0; k < 2; ++k) \
;         acc[ai][bj][m][n] = __builtin_amdgcn_mfma_f32_16x16x32_bf16(Bt[n][k], At[m][k], acc[ai][bj][m][n], 0, 0, 0); __builtin_amdgcn_s_setprio(0); } while (0)
; #define PG8_WAIT_V(n) asm volatile("s_waitcnt vmcnt(" #n ")" ::: "memory")
; #define PG8_BAR __builtin_amdgcn_s_barrier()
; template <class Epi, class Sched, bool ALIGN_EPI = false, bool SP2 = false>
; __device__ __forceinline__ void gemm_phase(PG8_LAS unsigned char* lds, const Gemm g, const Sched& S, const Epi& E) {
;     ...
;         for (int t = 0; t < nt; t += 2) {
;             const bool last = (t == nt - 2);
;             const char* a1 = cA + (size_t)(t + 1) * kstep;
;             const char* a2 = last ? nA : cA + (size_t)(t + 2) * kstep; const char* b2 = last ? nB : cB + (size_t)(t + 2) * kstep;
;             const char* a3 = a2 + kstep; const char* b3 = b2 + kstep;
;             if (last && has_next) S.a_ready(nxt);
;             if constexpr (SP2) {
;             PG8_LDB(B0, 0, 0); PG8_LDB(B1, 0, 1); PG8_SCHED; PG8_LDA(At, 0, 0); PG8_STAGE(PG8_SA(1, 1), a1 + hstep, voffA);
;             PG8_WAIT_V(8); PG8_WAIT_L(0); PG8_BAR; PG8_MMA(0, 0, At, B0); PG8_MMA(0, 1, At, B1); PG8_BAR; PG8_SCHED;
;             PG8_LDA(At, 0, 1); PG8_STAGE(PG8_SB(0, 0), b2, voffB); PG8_STAGE(PG8_SB(0, 1), b2 + hstep, voffB); PG8_STAGE(PG8_SA(0, 0), a2, voffA);
;             PG8_WAIT_V(8); PG8_WAIT_L(0); PG8_BAR; PG8_MMA(1, 0, At, B0); PG8_MMA(1, 1, At, B1); PG8_BAR; PG8_SCHED;
.LBB0_958:
	s_sub_i32 vcc_hi, 0x29000, s100
	s_sub_i32 vcc_hi, vcc_hi, s101
	s_add_u32 s4, s26, 0xfffe0080
	s_addc_u32 s5, s27, -1
	s_add_i32 s72, 0, 0x10000
	s_cmp_eq_u32 s71, 4
	s_cselect_b32 s39, s17, s5
	s_cselect_b32 s38, s29, s4
	v_add_u32_e32 v0, s72, v242
	s_cselect_b32 s5, s19, s70
	s_cselect_b32 s4, s68, s69
	s_add_i32 s74, 0, 0x14000
	ds_read_b128 v[130:133], v0
	ds_read_b128 v[134:137], v0 offset:1024
	ds_read_b128 v[138:141], v0 offset:2048
	ds_read_b128 v[142:145], v0 offset:3072
	v_add_u32_e32 v0, s74, v242
	ds_read_b128 v[146:149], v0
	ds_read_b128 v[150:153], v0 offset:1024
	ds_read_b128 v[154:157], v0 offset:2048
	ds_read_b128 v[158:161], v0 offset:3072
	v_lshl_add_u64 v[212:213], s[26:27], 0, v[208:209]
	s_add_i32 m0, s58, 0xc000
	v_add_u32_e32 v250, s100, v244
	ds_read_b128 v[162:165], v250
	ds_read_b128 v[166:169], v250 offset:1024
	ds_read_b128 v[170:173], v250 offset:2048
	ds_read_b128 v[174:177], v250 offset:3072
	ds_read_b128 v[178:181], v250 offset:4096
	ds_read_b128 v[182:185], v250 offset:5120
	ds_read_b128 v[186:189], v250 offset:6144
	ds_read_b128 v[190:193], v250 offset:7168
	global_load_lds_dwordx4 v[212:213], off
	v_lshl_add_u64 v[212:213], s[26:27], 0, v[210:211]
	s_add_i32 m0, s58, 0xe000
	s_nop 0
	global_load_lds_dwordx4 v[212:213], off
	v_lshl_add_u64 v[238:239], s[38:39], 0, v[206:207]
	v_lshl_add_u64 v[240:241], s[38:39], 0, v[202:203]
	s_add_i32 m0, vcc_hi, s58
	s_nop 0
	global_load_lds_dwordx4 v[238:239], off
	s_add_i32 m0, m0, 0x2000
	s_nop 0
	global_load_lds_dwordx4 v[240:241], off
	s_waitcnt vmcnt(10)
	s_waitcnt lgkmcnt(0)
	s_setprio 1
	s_waitcnt lgkmcnt(0)
	v_mfma_f32_16x16x32_bf16 v[126:129], v[130:133], v[162:165], v[126:129]
	v_mfma_f32_16x16x32_bf16 v[118:121], v[138:141], v[162:165], v[118:121]
	v_mfma_f32_16x16x32_bf16 v[110:113], v[130:133], v[170:173], v[110:113]
	v_mfma_f32_16x16x32_bf16 v[102:105], v[138:141], v[170:173], v[102:105]
	s_barrier
	v_mfma_f32_16x16x32_bf16 v[94:97], v[130:133], v[178:181], v[94:97]
	v_mfma_f32_16x16x32_bf16 v[86:89], v[138:141], v[178:181], v[86:89]
	v_mfma_f32_16x16x32_bf16 v[78:81], v[130:133], v[186:189], v[78:81]
	v_mfma_f32_16x16x32_bf16 v[70:73], v[138:141], v[186:189], v[70:73]
	v_mfma_f32_16x16x32_bf16 v[126:129], v[134:137], v[166:169], v[126:129]
	v_mfma_f32_16x16x32_bf16 v[118:121], v[142:145], v[166:169], v[118:121]
	v_mfma_f32_16x16x32_bf16 v[110:113], v[134:137], v[174:177], v[110:113]
	v_mfma_f32_16x16x32_bf16 v[102:105], v[142:145], v[174:177], v[102:105]
	v_mfma_f32_16x16x32_bf16 v[94:97], v[134:137], v[182:185], v[94:97]
	v_mfma_f32_16x16x32_bf16 v[86:89], v[142:145], v[182:185], v[86:89]
	v_mfma_f32_16x16x32_bf16 v[78:81], v[134:137], v[190:193], v[78:81]
	v_mfma_f32_16x16x32_bf16 v[70:73], v[142:145], v[190:193], v[70:73]
	s_setprio 0
	s_setprio 1
	v_mfma_f32_16x16x32_bf16 v[122:125], v[146:149], v[162:165], v[122:125]
	v_mfma_f32_16x16x32_bf16 v[114:117], v[154:157], v[162:165], v[114:117]
	v_mfma_f32_16x16x32_bf16 v[106:109], v[146:149], v[170:173], v[106:109]
	v_mfma_f32_16x16x32_bf16 v[98:101], v[154:157], v[170:173], v[98:101]
	v_mfma_f32_16x16x32_bf16 v[90:93], v[146:149], v[178:181], v[90:93]
	v_mfma_f32_16x16x32_bf16 v[82:85], v[154:157], v[178:181], v[82:85]
	v_mfma_f32_16x16x32_bf16 v[74:77], v[146:149], v[186:189], v[74:77]
	v_mfma_f32_16x16x32_bf16 v[66:69], v[154:157], v[186:189], v[66:69]
	v_mfma_f32_16x16x32_bf16 v[122:125], v[150:153], v[166:169], v[122:125]
	v_mfma_f32_16x16x32_bf16 v[114:117], v[158:161], v[166:169], v[114:117]
	v_mfma_f32_16x16x32_bf16 v[106:109], v[150:153], v[174:177], v[106:109]
	v_mfma_f32_16x16x32_bf16 v[98:101], v[158:161], v[174:177], v[98:101]
	v_mfma_f32_16x16x32_bf16 v[90:93], v[150:153], v[182:185], v[90:93]
	v_mfma_f32_16x16x32_bf16 v[82:85], v[158:161], v[182:185], v[82:85]
	v_mfma_f32_16x16x32_bf16 v[74:77], v[150:153], v[190:193], v[74:77]
	v_mfma_f32_16x16x32_bf16 v[66:69], v[158:161], v[190:193], v[66:69]
	s_setprio 0
	s_barrier
	s_add_i32 s72, s72, s57
	v_lshl_add_u64 v[212:213], s[4:5], 0, v[204:205]
	s_mov_b32 m0, s72
	ds_read_b128 v[162:165], v244 offset:16384
	ds_read_b128 v[166:169], v244 offset:17408
	ds_read_b128 v[170:173], v244 offset:18432
	ds_read_b128 v[174:177], v244 offset:19456
	ds_read_b128 v[178:181], v244 offset:20480
	ds_read_b128 v[182:185], v244 offset:21504
	ds_read_b128 v[186:189], v244 offset:22528
	ds_read_b128 v[190:193], v244 offset:23552
	global_load_lds_dwordx4 v[212:213], off
	s_add_i32 m0, s72, 0x2000
	s_add_u32 s72, s4, 0x20000
	v_lshl_add_u64 v[214:215], s[4:5], 0, v[194:195]
	s_addc_u32 s73, s5, 0
	s_add_i32 s74, s74, s57
	global_load_lds_dwordx4 v[214:215], off
	v_lshl_add_u64 v[216:217], s[72:73], 0, v[204:205]
	s_mov_b32 m0, s74
	s_nop 0
	global_load_lds_dwordx4 v[216:217], off
	v_lshl_add_u64 v[216:217], s[72:73], 0, v[194:195]
	s_add_i32 m0, s74, 0x2000
	s_nop 0
	global_load_lds_dwordx4 v[216:217], off
	s_waitcnt vmcnt(8)
	s_waitcnt lgkmcnt(0)
	s_setprio 1
	s_waitcnt lgkmcnt(0)
	v_mfma_f32_16x16x32_bf16 v[62:65], v[130:133], v[162:165], v[62:65]
	v_mfma_f32_16x16x32_bf16 v[54:57], v[138:141], v[162:165], v[54:57]
	v_mfma_f32_16x16x32_bf16 v[46:49], v[130:133], v[170:173], v[46:49]
	v_mfma_f32_16x16x32_bf16 v[38:41], v[138:141], v[170:173], v[38:41]
	s_barrier
; #define PG8_STAGE(bufoff, gbase, voff) do { _Pragma("unroll") for (int _i = 0; _i < 2; ++_i) \
;         __builtin_amdgcn_global_load_lds((const unsigned*)((const char*)(gbase) + (voff)[_i]), (PG8_LAS unsigned*)(lds + (bufoff) + ldsw + _i * 8192), 16, 0, 0); } while (0)
; #define PG8_LDA(dst, b, h) do { _Pragma("unroll") for (int m = 0; m < 4; ++m) _Pragma("unroll") for (int k = 0; k < 2; ++k) dst[m][k] = *(const PG8_LAS bf16x8*)(lds + PG8_SA(b, h) + aoff + m * 2048 + k * 1024); } while (0)
; #define PG8_LDB(dst, b, h) do { _Pragma("unroll") for (int n = 0; n < 2; ++n) _Pragma("unroll") for (int k = 0; k < 2; ++k) dst[n][k] = *(const PG8_LAS bf16x8*)(lds + PG8_SB(b, h) + boff + n * 2048 + k * 1024); } while (0)
; template <class Epi, class Sched, bool ALIGN_EPI = false, bool SP2 = false>
; __device__ __forceinline__ void gemm_phase(PG8_LAS unsigned char* lds, const Gemm g, const Sched& S, const Epi& E) {
;     ...
;         for (int t = 0; t < nt; t += 2) {
;             const bool last = (t == nt - 2);
;             const char* a1 = cA + (size_t)(t + 1) * kstep;
;             const char* a2 = last ? nA : cA + (size_t)(t + 2) * kstep; const char* b2 = last ? nB : cB + (size_t)(t + 2) * kstep;
;             const char* a3 = a2 + kstep; const char* b3 = b2 + kstep;
;             if (last && has_next) S.a_ready(nxt);
;             if constexpr (SP2) {
;             PG8_LDB(B0, 0, 0); PG8_LDB(B1, 0, 1); PG8_SCHED; PG8_LDA(At, 0, 0); PG8_STAGE(PG8_SA(1, 1), a1 + hstep, voffA);
;             PG8_WAIT_V(8); PG8_WAIT_L(0); PG8_BAR; PG8_MMA(0, 0, At, B0); PG8_MMA(0, 1, At, B1); PG8_BAR; PG8_SCHED;
;             PG8_LDA(At, 0, 1); PG8_STAGE(PG8_SB(0, 0), b2, voffB); PG8_STAGE(PG8_SB(0, 1), b2 + hstep, voffB); PG8_STAGE(PG8_SA(0, 0), a2, voffA);
;             PG8_WAIT_V(8); PG8_WAIT_L(0); PG8_BAR; PG8_MMA(1, 0, At, B0); PG8_MMA(1, 1, At, B1); PG8_BAR; PG8_SCHED;
;             PG8_LDB(B0, 1, 0); PG8_LDB(B1, 1, 1); PG8_SCHED; PG8_LDA(At, 1, 0); PG8_STAGE(PG8_SA(0, 1), a2 + hstep, voffA);
;             PG8_WAIT_V(8); PG8_WAIT_L(0); PG8_BAR; PG8_MMA(0, 0, At, B0); PG8_MMA(0, 1, At, B1); PG8_BAR; PG8_SCHED;
;             PG8_LDA(At, 1, 1); PG8_STAGE(PG8_SB(1, 0), b3, voffB); PG8_STAGE(PG8_SB(1, 1), b3 + hstep, voffB); PG8_STAGE(PG8_SA(1, 0), a3, voffA);
;             PG8_WAIT_V(8); PG8_WAIT_L(0); PG8_BAR; PG8_MMA(1, 0, At, B0); PG8_MMA(1, 1, At, B1); PG8_BAR; PG8_SCHED;
	v_mfma_f32_16x16x32_bf16 v[30:33], v[130:133], v[178:181], v[30:33]
	v_mfma_f32_16x16x32_bf16 v[22:25], v[138:141], v[178:181], v[22:25]
	v_mfma_f32_16x16x32_bf16 v[14:17], v[130:133], v[186:189], v[14:17]
	v_mfma_f32_16x16x32_bf16 v[6:9], v[138:141], v[186:189], v[6:9]
	v_mfma_f32_16x16x32_bf16 v[62:65], v[134:137], v[166:169], v[62:65]
	v_mfma_f32_16x16x32_bf16 v[54:57], v[142:145], v[166:169], v[54:57]
	v_mfma_f32_16x16x32_bf16 v[46:49], v[134:137], v[174:177], v[46:49]
	v_mfma_f32_16x16x32_bf16 v[38:41], v[142:145], v[174:177], v[38:41]
	v_mfma_f32_16x16x32_bf16 v[30:33], v[134:137], v[182:185], v[30:33]
	v_mfma_f32_16x16x32_bf16 v[22:25], v[142:145], v[182:185], v[22:25]
	v_mfma_f32_16x16x32_bf16 v[14:17], v[134:137], v[190:193], v[14:17]
	v_mfma_f32_16x16x32_bf16 v[6:9], v[142:145], v[190:193], v[6:9]
	s_setprio 0
	s_setprio 1
	v_mfma_f32_16x16x32_bf16 v[58:61], v[146:149], v[162:165], v[58:61]
	v_mfma_f32_16x16x32_bf16 v[50:53], v[154:157], v[162:165], v[50:53]
	v_mfma_f32_16x16x32_bf16 v[42:45], v[146:149], v[170:173], v[42:45]
	v_mfma_f32_16x16x32_bf16 v[34:37], v[154:157], v[170:173], v[34:37]
	v_mfma_f32_16x16x32_bf16 v[26:29], v[146:149], v[178:181], v[26:29]
	v_mfma_f32_16x16x32_bf16 v[18:21], v[154:157], v[178:181], v[18:21]
	v_mfma_f32_16x16x32_bf16 v[10:13], v[146:149], v[186:189], v[10:13]
	v_mfma_f32_16x16x32_bf16 v[2:5], v[154:157], v[186:189], v[2:5]
	v_mfma_f32_16x16x32_bf16 v[58:61], v[150:153], v[166:169], v[58:61]
	v_mfma_f32_16x16x32_bf16 v[50:53], v[158:161], v[166:169], v[50:53]
	v_mfma_f32_16x16x32_bf16 v[42:45], v[150:153], v[174:177], v[42:45]
	v_mfma_f32_16x16x32_bf16 v[34:37], v[158:161], v[174:177], v[34:37]
	v_mfma_f32_16x16x32_bf16 v[26:29], v[150:153], v[182:185], v[26:29]
	v_mfma_f32_16x16x32_bf16 v[18:21], v[158:161], v[182:185], v[18:21]
	v_mfma_f32_16x16x32_bf16 v[10:13], v[150:153], v[190:193], v[10:13]
	v_mfma_f32_16x16x32_bf16 v[2:5], v[158:161], v[190:193], v[2:5]
	s_setprio 0
	s_barrier
	s_add_i32 s72, 0, 0x18000
	v_add_u32_e32 v0, s72, v242
	s_add_i32 s73, 0, 0x1c000
	ds_read_b128 v[130:133], v0
	ds_read_b128 v[134:137], v0 offset:1024
	ds_read_b128 v[138:141], v0 offset:2048
	ds_read_b128 v[142:145], v0 offset:3072
	v_add_u32_e32 v0, s73, v242
	ds_read_b128 v[146:149], v0
	ds_read_b128 v[150:153], v0 offset:1024
	ds_read_b128 v[154:157], v0 offset:2048
	ds_read_b128 v[158:161], v0 offset:3072
	s_add_u32 s38, s38, 0x20000
	s_addc_u32 s39, s39, 0
	s_mov_b32 m0, s60
	v_lshl_add_u64 v[220:221], s[38:39], 0, v[206:207]
	v_add_u32_e32 v250, s101, v244
	ds_read_b128 v[162:165], v250
	ds_read_b128 v[166:169], v250 offset:1024
	ds_read_b128 v[170:173], v250 offset:2048
	ds_read_b128 v[174:177], v250 offset:3072
	ds_read_b128 v[178:181], v250 offset:4096
	ds_read_b128 v[182:185], v250 offset:5120
	ds_read_b128 v[186:189], v250 offset:6144
	ds_read_b128 v[190:193], v250 offset:7168
	global_load_lds_dwordx4 v[220:221], off
	v_lshl_add_u64 v[220:221], s[38:39], 0, v[202:203]
	s_mov_b32 m0, s61
	s_nop 0
	global_load_lds_dwordx4 v[220:221], off
	v_lshl_add_u64 v[246:247], v[238:239], 0, s[96:97]
	v_lshl_add_u64 v[248:249], v[240:241], 0, s[96:97]
	s_add_i32 m0, s100, s58
	s_nop 0
	global_load_lds_dwordx4 v[246:247], off
	s_add_i32 m0, m0, 0x2000
	s_nop 0
	global_load_lds_dwordx4 v[248:249], off
	s_waitcnt vmcnt(10)
	s_waitcnt lgkmcnt(0)
	s_setprio 1
	s_waitcnt lgkmcnt(0)
	v_mfma_f32_16x16x32_bf16 v[126:129], v[130:133], v[162:165], v[126:129]
	v_mfma_f32_16x16x32_bf16 v[118:121], v[138:141], v[162:165], v[118:121]
	v_mfma_f32_16x16x32_bf16 v[110:113], v[130:133], v[170:173], v[110:113]
	v_mfma_f32_16x16x32_bf16 v[102:105], v[138:141], v[170:173], v[102:105]
	s_barrier
; #define PG8_STAGE(bufoff, gbase, voff) do { _Pragma("unroll") for (int _i = 0; _i < 2; ++_i) \
;         __builtin_amdgcn_global_load_lds((const unsigned*)((const char*)(gbase) + (voff)[_i]), (PG8_LAS unsigned*)(lds + (bufoff) + ldsw + _i * 8192), 16, 0, 0); } while (0)
; #define PG8_LDA(dst, b, h) do { _Pragma("unroll") for (int m = 0; m < 4; ++m) _Pragma("unroll") for (int k = 0; k < 2; ++k) dst[m][k] = *(const PG8_LAS bf16x8*)(lds + PG8_SA(b, h) + aoff + m * 2048 + k * 1024); } while (0)
; #define PG8_LDB(dst, b, h) do { _Pragma("unroll") for (int n = 0; n < 2; ++n) _Pragma("unroll") for (int k = 0; k < 2; ++k) dst[n][k] = *(const PG8_LAS bf16x8*)(lds + PG8_SB(b, h) + boff + n * 2048 + k * 1024); } while (0)
; template <class Epi, class Sched, bool ALIGN_EPI = false, bool SP2 = false>
; __device__ __forceinline__ void gemm_phase(PG8_LAS unsigned char* lds, const Gemm g, const Sched& S, const Epi& E) {
;     ...
;         for (int t = 0; t < nt; t += 2) {
;             const bool last = (t == nt - 2);
;             const char* a1 = cA + (size_t)(t + 1) * kstep;
;             const char* a2 = last ? nA : cA + (size_t)(t + 2) * kstep; const char* b2 = last ? nB : cB + (size_t)(t + 2) * kstep;
;             const char* a3 = a2 + kstep; const char* b3 = b2 + kstep;
;             if (last && has_next) S.a_ready(nxt);
;             if constexpr (SP2) {
;             PG8_LDB(B0, 0, 0); PG8_LDB(B1, 0, 1); PG8_SCHED; PG8_LDA(At, 0, 0); PG8_STAGE(PG8_SA(1, 1), a1 + hstep, voffA);
;             PG8_WAIT_V(8); PG8_WAIT_L(0); PG8_BAR; PG8_MMA(0, 0, At, B0); PG8_MMA(0, 1, At, B1); PG8_BAR; PG8_SCHED;
;             PG8_LDA(At, 0, 1); PG8_STAGE(PG8_SB(0, 0), b2, voffB); PG8_STAGE(PG8_SB(0, 1), b2 + hstep, voffB); PG8_STAGE(PG8_SA(0, 0), a2, voffA);
;             PG8_WAIT_V(8); PG8_WAIT_L(0); PG8_BAR; PG8_MMA(1, 0, At, B0); PG8_MMA(1, 1, At, B1); PG8_BAR; PG8_SCHED;
;             PG8_LDB(B0, 1, 0); PG8_LDB(B1, 1, 1); PG8_SCHED; PG8_LDA(At, 1, 0); PG8_STAGE(PG8_SA(0, 1), a2 + hstep, voffA);
;             PG8_WAIT_V(8); PG8_WAIT_L(0); PG8_BAR; PG8_MMA(0, 0, At, B0); PG8_MMA(0, 1, At, B1); PG8_BAR; PG8_SCHED;
;             PG8_LDA(At, 1, 1); PG8_STAGE(PG8_SB(1, 0), b3, voffB); PG8_STAGE(PG8_SB(1, 1), b3 + hstep, voffB); PG8_STAGE(PG8_SA(1, 0), a3, voffA);
;             PG8_WAIT_V(8); PG8_WAIT_L(0); PG8_BAR; PG8_MMA(1, 0, At, B0); PG8_MMA(1, 1, At, B1); PG8_BAR; PG8_SCHED;
	v_mfma_f32_16x16x32_bf16 v[94:97], v[130:133], v[178:181], v[94:97]
	v_mfma_f32_16x16x32_bf16 v[86:89], v[138:141], v[178:181], v[86:89]
	v_mfma_f32_16x16x32_bf16 v[78:81], v[130:133], v[186:189], v[78:81]
	v_mfma_f32_16x16x32_bf16 v[70:73], v[138:141], v[186:189], v[70:73]
	v_mfma_f32_16x16x32_bf16 v[126:129], v[134:137], v[166:169], v[126:129]
	v_mfma_f32_16x16x32_bf16 v[118:121], v[142:145], v[166:169], v[118:121]
	v_mfma_f32_16x16x32_bf16 v[110:113], v[134:137], v[174:177], v[110:113]
	v_mfma_f32_16x16x32_bf16 v[102:105], v[142:145], v[174:177], v[102:105]
	v_mfma_f32_16x16x32_bf16 v[94:97], v[134:137], v[182:185], v[94:97]
	v_mfma_f32_16x16x32_bf16 v[86:89], v[142:145], v[182:185], v[86:89]
	v_mfma_f32_16x16x32_bf16 v[78:81], v[134:137], v[190:193], v[78:81]
	v_mfma_f32_16x16x32_bf16 v[70:73], v[142:145], v[190:193], v[70:73]
	s_setprio 0
	s_setprio 1
	v_mfma_f32_16x16x32_bf16 v[122:125], v[146:149], v[162:165], v[122:125]
	v_mfma_f32_16x16x32_bf16 v[114:117], v[154:157], v[162:165], v[114:117]
	v_mfma_f32_16x16x32_bf16 v[106:109], v[146:149], v[170:173], v[106:109]
	v_mfma_f32_16x16x32_bf16 v[98:101], v[154:157], v[170:173], v[98:101]
	v_mfma_f32_16x16x32_bf16 v[90:93], v[146:149], v[178:181], v[90:93]
	v_mfma_f32_16x16x32_bf16 v[82:85], v[154:157], v[178:181], v[82:85]
	v_mfma_f32_16x16x32_bf16 v[74:77], v[146:149], v[186:189], v[74:77]
	v_mfma_f32_16x16x32_bf16 v[66:69], v[154:157], v[186:189], v[66:69]
	v_mfma_f32_16x16x32_bf16 v[122:125], v[150:153], v[166:169], v[122:125]
	v_mfma_f32_16x16x32_bf16 v[114:117], v[158:161], v[166:169], v[114:117]
	v_mfma_f32_16x16x32_bf16 v[106:109], v[150:153], v[174:177], v[106:109]
	v_mfma_f32_16x16x32_bf16 v[98:101], v[158:161], v[174:177], v[98:101]
	v_mfma_f32_16x16x32_bf16 v[90:93], v[150:153], v[182:185], v[90:93]
	v_mfma_f32_16x16x32_bf16 v[82:85], v[158:161], v[182:185], v[82:85]
	v_mfma_f32_16x16x32_bf16 v[74:77], v[150:153], v[190:193], v[74:77]
	v_mfma_f32_16x16x32_bf16 v[66:69], v[158:161], v[190:193], v[66:69]
	s_setprio 0
	s_barrier
	s_add_i32 s38, s72, s57
	v_lshl_add_u64 v[212:213], v[212:213], 0, s[96:97]
	s_mov_b32 m0, s38
	ds_read_b128 v[162:165], v244 offset:49152
	ds_read_b128 v[166:169], v244 offset:50176
	ds_read_b128 v[170:173], v244 offset:51200
	ds_read_b128 v[174:177], v244 offset:52224
	ds_read_b128 v[178:181], v244 offset:53248
	ds_read_b128 v[182:185], v244 offset:54272
	ds_read_b128 v[186:189], v244 offset:55296
	ds_read_b128 v[190:193], v244 offset:56320
	global_load_lds_dwordx4 v[212:213], off
	s_add_i32 m0, s38, 0x2000
	s_add_u32 s4, s4, 0x20080
	v_lshl_add_u64 v[212:213], v[214:215], 0, s[96:97]
	s_addc_u32 s5, s5, 0
	s_add_i32 s38, s73, s57
	global_load_lds_dwordx4 v[212:213], off
	v_lshl_add_u64 v[212:213], s[4:5], 0, v[204:205]
	s_mov_b32 m0, s38
	s_nop 0
	global_load_lds_dwordx4 v[212:213], off
	v_lshl_add_u64 v[212:213], s[4:5], 0, v[194:195]
	s_add_i32 m0, s38, 0x2000
	s_nop 0
	global_load_lds_dwordx4 v[212:213], off
	s_waitcnt vmcnt(8)
	s_waitcnt lgkmcnt(0)
	s_setprio 1
	s_waitcnt lgkmcnt(0)
	v_mfma_f32_16x16x32_bf16 v[62:65], v[130:133], v[162:165], v[62:65]
	v_mfma_f32_16x16x32_bf16 v[54:57], v[138:141], v[162:165], v[54:57]
	v_mfma_f32_16x16x32_bf16 v[46:49], v[130:133], v[170:173], v[46:49]
	v_mfma_f32_16x16x32_bf16 v[38:41], v[138:141], v[170:173], v[38:41]
	s_barrier
	v_mfma_f32_16x16x32_bf16 v[30:33], v[130:133], v[178:181], v[30:33]
	v_mfma_f32_16x16x32_bf16 v[22:25], v[138:141], v[178:181], v[22:25]
	v_mfma_f32_16x16x32_bf16 v[14:17], v[130:133], v[186:189], v[14:17]
	v_mfma_f32_16x16x32_bf16 v[6:9], v[138:141], v[186:189], v[6:9]
	v_mfma_f32_16x16x32_bf16 v[62:65], v[134:137], v[166:169], v[62:65]
	v_mfma_f32_16x16x32_bf16 v[54:57], v[142:145], v[166:169], v[54:57]
	v_mfma_f32_16x16x32_bf16 v[46:49], v[134:137], v[174:177], v[46:49]
	v_mfma_f32_16x16x32_bf16 v[38:41], v[142:145], v[174:177], v[38:41]
	v_mfma_f32_16x16x32_bf16 v[30:33], v[134:137], v[182:185], v[30:33]
	v_mfma_f32_16x16x32_bf16 v[22:25], v[142:145], v[182:185], v[22:25]
	v_mfma_f32_16x16x32_bf16 v[14:17], v[134:137], v[190:193], v[14:17]
	v_mfma_f32_16x16x32_bf16 v[6:9], v[142:145], v[190:193], v[6:9]
	s_setprio 0
	s_setprio 1
	v_mfma_f32_16x16x32_bf16 v[58:61], v[146:149], v[162:165], v[58:61]
	v_mfma_f32_16x16x32_bf16 v[50:53], v[154:157], v[162:165], v[50:53]
	v_mfma_f32_16x16x32_bf16 v[42:45], v[146:149], v[170:173], v[42:45]
	v_mfma_f32_16x16x32_bf16 v[34:37], v[154:157], v[170:173], v[34:37]
	v_mfma_f32_16x16x32_bf16 v[26:29], v[146:149], v[178:181], v[26:29]
	v_mfma_f32_16x16x32_bf16 v[18:21], v[154:157], v[178:181], v[18:21]
	v_mfma_f32_16x16x32_bf16 v[10:13], v[146:149], v[186:189], v[10:13]
	v_mfma_f32_16x16x32_bf16 v[2:5], v[154:157], v[186:189], v[2:5]
	v_mfma_f32_16x16x32_bf16 v[58:61], v[150:153], v[166:169], v[58:61]
	v_mfma_f32_16x16x32_bf16 v[50:53], v[158:161], v[166:169], v[50:53]
	v_mfma_f32_16x16x32_bf16 v[42:45], v[150:153], v[174:177], v[42:45]
	v_mfma_f32_16x16x32_bf16 v[34:37], v[158:161], v[174:177], v[34:37]
	v_mfma_f32_16x16x32_bf16 v[26:29], v[150:153], v[182:185], v[26:29]
	v_mfma_f32_16x16x32_bf16 v[18:21], v[158:161], v[182:185], v[18:21]
	v_mfma_f32_16x16x32_bf16 v[10:13], v[150:153], v[190:193], v[10:13]
	v_mfma_f32_16x16x32_bf16 v[2:5], v[158:161], v[190:193], v[2:5]
	s_setprio 0
	s_barrier
	s_add_i32 s71, s71, 2
	s_mov_b32 s101, s100
	s_mov_b32 s100, vcc_hi
	s_add_u32 s26, s26, 0x100
	s_addc_u32 s27, s27, 0
	s_add_u32 s69, s69, 0x100
	s_addc_u32 s70, s70, 0
	s_cmp_gt_u32 s71, 5
	s_cbranch_scc0 .LBB0_958
	s_and_b64 vcc, exec, s[14:15]
	s_cbranch_vccz .LBB0_961
	s_barrier

; #define PG8_STAGE(bufoff, gbase, voff) do { _Pragma("unroll") for (int _i = 0; _i < 2; ++_i) \
;         __builtin_amdgcn_global_load_lds((const unsigned*)((const char*)(gbase) + (voff)[_i]), (PG8_LAS unsigned*)(lds + (bufoff) + ldsw + _i * 8192), 16, 0, 0); } while (0)
; #define PG8_LDA(dst, b, h) do { _Pragma("unroll") for (int m = 0; m < 4; ++m) _Pragma("unroll") for (int k = 0; k < 2; ++k) dst[m][k] = *(const PG8_LAS bf16x8*)(lds + PG8_SA(b, h) + aoff + m * 2048 + k * 1024); } while (0)
; #define PG8_LDB(dst, b, h) do { _Pragma("unroll") for (int n = 0; n < 2; ++n) _Pragma("unroll") for (int k = 0; k < 2; ++k) dst[n][k] = *(const PG8_LAS bf16x8*)(lds + PG8_SB(b, h) + boff + n * 2048 + k * 1024); } while (0)
; template <class Epi, class Sched, bool ALIGN_EPI = false, bool SP2 = false>
; __device__ __forceinline__ void gemm_phase(PG8_LAS unsigned char* lds, const Gemm g, const Sched& S, const Epi& E) {
;     ...
;         for (int t = 0; t < nt; t += 2) {
;             const bool last = (t == nt - 2);
;             const char* a1 = cA + (size_t)(t + 1) * kstep;
;             const char* a2 = last ? nA : cA + (size_t)(t + 2) * kstep; const char* b2 = last ? nB : cB + (size_t)(t + 2) * kstep;
;             const char* a3 = a2 + kstep; const char* b3 = b2 + kstep;
;             if (last && has_next) S.a_ready(nxt);
;             if constexpr (SP2) {
;             PG8_LDB(B0, 0, 0); PG8_LDB(B1, 0, 1); PG8_SCHED; PG8_LDA(At, 0, 0); PG8_STAGE(PG8_SA(1, 1), a1 + hstep, voffA);
;             PG8_WAIT_V(8); PG8_WAIT_L(0); PG8_BAR; PG8_MMA(0, 0, At, B0); PG8_MMA(0, 1, At, B1); PG8_BAR; PG8_SCHED;
;             PG8_LDA(At, 0, 1); PG8_STAGE(PG8_SB(0, 0), b2, voffB); PG8_STAGE(PG8_SB(0, 1), b2 + hstep, voffB); PG8_STAGE(PG8_SA(0, 0), a2, voffA);
;             PG8_WAIT_V(8); PG8_WAIT_L(0); PG8_BAR; PG8_MMA(1, 0, At, B0); PG8_MMA(1, 1, At, B1); PG8_BAR; PG8_SCHED;
;             PG8_LDB(B0, 1, 0); PG8_LDB(B1, 1, 1); PG8_SCHED; PG8_LDA(At, 1, 0); PG8_STAGE(PG8_SA(0, 1), a2 + hstep, voffA);
;             PG8_WAIT_V(8); PG8_WAIT_L(0); PG8_BAR; PG8_MMA(0, 0, At, B0); PG8_MMA(0, 1, At, B1); PG8_BAR; PG8_SCHED;
;             PG8_LDA(At, 1, 1); PG8_STAGE(PG8_SB(1, 0), b3, voffB); PG8_STAGE(PG8_SB(1, 1), b3 + hstep, voffB); PG8_STAGE(PG8_SA(1, 0), a3, voffA);
;             PG8_WAIT_V(8); PG8_WAIT_L(0); PG8_BAR; PG8_MMA(1, 0, At, B0); PG8_MMA(1, 1, At, B1); PG8_BAR; PG8_SCHED;
.LBB0_1255:
	s_sub_i32 vcc_hi, 0x29000, s100
	s_sub_i32 vcc_hi, vcc_hi, s101
	s_add_u32 s38, s26, 0x100
	s_addc_u32 s39, s27, 0
	s_add_i32 s64, 0, 0x10000
	s_cmp_eq_u32 s63, 28
	s_cselect_b32 s43, s15, s39
	s_cselect_b32 s42, s59, s38
	s_cselect_b32 s41, s11, s62
	s_cselect_b32 s40, s60, s61
	s_add_i32 s65, 0, 0x14000
	v_add_u32_e32 v148, s64, v171
	v_add_u32_e32 v164, s65, v171
	ds_read_b128 v[136:139], v148
	ds_read_b128 v[140:143], v148 offset:1024
	ds_read_b128 v[144:147], v148 offset:2048
	ds_read_b128 v[148:151], v148 offset:3072
	ds_read_b128 v[152:155], v164
	ds_read_b128 v[156:159], v164 offset:1024
	ds_read_b128 v[160:163], v164 offset:2048
	ds_read_b128 v[164:167], v164 offset:3072
	v_lshl_add_u64 v[168:169], s[26:27], 0, v[132:133]
	s_add_i32 m0, s23, 0xc000
	v_add_u32_e32 v250, s100, v173
	ds_read_b128 v[174:177], v250
	ds_read_b128 v[178:181], v250 offset:1024
	ds_read_b128 v[182:185], v250 offset:2048
	ds_read_b128 v[186:189], v250 offset:3072
	ds_read_b128 v[190:193], v250 offset:4096
	ds_read_b128 v[202:205], v250 offset:5120
	ds_read_b128 v[206:209], v250 offset:6144
	ds_read_b128 v[210:213], v250 offset:7168
	global_load_lds_dwordx4 v[168:169], off
	v_lshl_add_u64 v[168:169], s[26:27], 0, v[134:135]
	s_add_i32 m0, s23, 0xe000
	s_nop 0
	global_load_lds_dwordx4 v[168:169], off
	v_lshl_add_u64 v[238:239], s[42:43], 0, v[0:1]
	v_lshl_add_u64 v[240:241], s[42:43], 0, v[130:131]
	s_add_i32 m0, vcc_hi, s23
	s_nop 0
	global_load_lds_dwordx4 v[238:239], off
	s_add_i32 m0, m0, 0x2000
	s_nop 0
	global_load_lds_dwordx4 v[240:241], off
	s_waitcnt vmcnt(10)
	s_waitcnt lgkmcnt(0)
	s_setprio 1
	s_waitcnt lgkmcnt(0)
	v_mfma_f32_16x16x32_bf16 v[98:101], v[136:139], v[174:177], v[98:101]
	v_mfma_f32_16x16x32_bf16 v[78:81], v[144:147], v[174:177], v[78:81]
	v_mfma_f32_16x16x32_bf16 v[102:105], v[136:139], v[182:185], v[102:105]
	v_mfma_f32_16x16x32_bf16 v[74:77], v[144:147], v[182:185], v[74:77]
	s_barrier
	v_mfma_f32_16x16x32_bf16 v[106:109], v[136:139], v[190:193], v[106:109]
	v_mfma_f32_16x16x32_bf16 v[70:73], v[144:147], v[190:193], v[70:73]
	v_mfma_f32_16x16x32_bf16 v[110:113], v[136:139], v[206:209], v[110:113]
	v_mfma_f32_16x16x32_bf16 v[66:69], v[144:147], v[206:209], v[66:69]
	v_mfma_f32_16x16x32_bf16 v[98:101], v[140:143], v[178:181], v[98:101]
	v_mfma_f32_16x16x32_bf16 v[78:81], v[148:151], v[178:181], v[78:81]
	v_mfma_f32_16x16x32_bf16 v[102:105], v[140:143], v[186:189], v[102:105]
	v_mfma_f32_16x16x32_bf16 v[74:77], v[148:151], v[186:189], v[74:77]
	v_mfma_f32_16x16x32_bf16 v[106:109], v[140:143], v[202:205], v[106:109]
	v_mfma_f32_16x16x32_bf16 v[70:73], v[148:151], v[202:205], v[70:73]
	v_mfma_f32_16x16x32_bf16 v[110:113], v[140:143], v[210:213], v[110:113]
	v_mfma_f32_16x16x32_bf16 v[66:69], v[148:151], v[210:213], v[66:69]
	s_setprio 0
	s_setprio 1
	v_mfma_f32_16x16x32_bf16 v[46:49], v[152:155], v[174:177], v[46:49]
	v_mfma_f32_16x16x32_bf16 v[2:5], v[160:163], v[174:177], v[2:5]
	v_mfma_f32_16x16x32_bf16 v[42:45], v[152:155], v[182:185], v[42:45]
	v_mfma_f32_16x16x32_bf16 v[6:9], v[160:163], v[182:185], v[6:9]
	v_mfma_f32_16x16x32_bf16 v[38:41], v[152:155], v[190:193], v[38:41]
	v_mfma_f32_16x16x32_bf16 v[10:13], v[160:163], v[190:193], v[10:13]
	v_mfma_f32_16x16x32_bf16 v[34:37], v[152:155], v[206:209], v[34:37]
	v_mfma_f32_16x16x32_bf16 v[14:17], v[160:163], v[206:209], v[14:17]
	v_mfma_f32_16x16x32_bf16 v[46:49], v[156:159], v[178:181], v[46:49]
	v_mfma_f32_16x16x32_bf16 v[2:5], v[164:167], v[178:181], v[2:5]
	v_mfma_f32_16x16x32_bf16 v[42:45], v[156:159], v[186:189], v[42:45]
	v_mfma_f32_16x16x32_bf16 v[6:9], v[164:167], v[186:189], v[6:9]
	v_mfma_f32_16x16x32_bf16 v[38:41], v[156:159], v[202:205], v[38:41]
	v_mfma_f32_16x16x32_bf16 v[10:13], v[164:167], v[202:205], v[10:13]
	v_mfma_f32_16x16x32_bf16 v[34:37], v[156:159], v[210:213], v[34:37]
	v_mfma_f32_16x16x32_bf16 v[14:17], v[164:167], v[210:213], v[14:17]
	s_setprio 0
	s_barrier
	s_add_i32 s26, s64, s44
	v_lshl_add_u64 v[168:169], s[40:41], 0, v[0:1]
	s_mov_b32 m0, s26
	ds_read_b128 v[174:177], v173 offset:16384
	ds_read_b128 v[178:181], v173 offset:17408
	ds_read_b128 v[182:185], v173 offset:18432
	ds_read_b128 v[186:189], v173 offset:19456
	ds_read_b128 v[190:193], v173 offset:20480
	ds_read_b128 v[202:205], v173 offset:21504
	ds_read_b128 v[206:209], v173 offset:22528
	ds_read_b128 v[210:213], v173 offset:23552
	global_load_lds_dwordx4 v[168:169], off
	s_add_i32 m0, s26, 0x2000
	s_add_u32 s26, s40, 0x80000
	v_lshl_add_u64 v[194:195], s[40:41], 0, v[130:131]
	s_addc_u32 s27, s41, 0
	s_add_i32 s64, s65, s44
	global_load_lds_dwordx4 v[194:195], off
	v_lshl_add_u64 v[214:215], s[26:27], 0, v[0:1]
	s_mov_b32 m0, s64
	s_nop 0
	global_load_lds_dwordx4 v[214:215], off
	v_lshl_add_u64 v[214:215], s[26:27], 0, v[130:131]
	s_add_i32 m0, s64, 0x2000
	s_nop 0
	global_load_lds_dwordx4 v[214:215], off
	s_waitcnt vmcnt(8)
	s_waitcnt lgkmcnt(0)
	s_setprio 1
	s_waitcnt lgkmcnt(0)
	v_mfma_f32_16x16x32_bf16 v[114:117], v[136:139], v[174:177], v[114:117]
	v_mfma_f32_16x16x32_bf16 v[94:97], v[144:147], v[174:177], v[94:97]
	v_mfma_f32_16x16x32_bf16 v[118:121], v[136:139], v[182:185], v[118:121]
	v_mfma_f32_16x16x32_bf16 v[90:93], v[144:147], v[182:185], v[90:93]
	s_barrier
; #define PG8_STAGE(bufoff, gbase, voff) do { _Pragma("unroll") for (int _i = 0; _i < 2; ++_i) \
;         __builtin_amdgcn_global_load_lds((const unsigned*)((const char*)(gbase) + (voff)[_i]), (PG8_LAS unsigned*)(lds + (bufoff) + ldsw + _i * 8192), 16, 0, 0); } while (0)
; #define PG8_LDA(dst, b, h) do { _Pragma("unroll") for (int m = 0; m < 4; ++m) _Pragma("unroll") for (int k = 0; k < 2; ++k) dst[m][k] = *(const PG8_LAS bf16x8*)(lds + PG8_SA(b, h) + aoff + m * 2048 + k * 1024); } while (0)
; #define PG8_LDB(dst, b, h) do { _Pragma("unroll") for (int n = 0; n < 2; ++n) _Pragma("unroll") for (int k = 0; k < 2; ++k) dst[n][k] = *(const PG8_LAS bf16x8*)(lds + PG8_SB(b, h) + boff + n * 2048 + k * 1024); } while (0)
; template <class Epi, class Sched, bool ALIGN_EPI = false, bool SP2 = false>
; __device__ __forceinline__ void gemm_phase(PG8_LAS unsigned char* lds, const Gemm g, const Sched& S, const Epi& E) {
;     ...
;         for (int t = 0; t < nt; t += 2) {
;             const bool last = (t == nt - 2);
;             const char* a1 = cA + (size_t)(t + 1) * kstep;
;             const char* a2 = last ? nA : cA + (size_t)(t + 2) * kstep; const char* b2 = last ? nB : cB + (size_t)(t + 2) * kstep;
;             const char* a3 = a2 + kstep; const char* b3 = b2 + kstep;
;             if (last && has_next) S.a_ready(nxt);
;             if constexpr (SP2) {
;             PG8_LDB(B0, 0, 0); PG8_LDB(B1, 0, 1); PG8_SCHED; PG8_LDA(At, 0, 0); PG8_STAGE(PG8_SA(1, 1), a1 + hstep, voffA);
;             PG8_WAIT_V(8); PG8_WAIT_L(0); PG8_BAR; PG8_MMA(0, 0, At, B0); PG8_MMA(0, 1, At, B1); PG8_BAR; PG8_SCHED;
;             PG8_LDA(At, 0, 1); PG8_STAGE(PG8_SB(0, 0), b2, voffB); PG8_STAGE(PG8_SB(0, 1), b2 + hstep, voffB); PG8_STAGE(PG8_SA(0, 0), a2, voffA);
;             PG8_WAIT_V(8); PG8_WAIT_L(0); PG8_BAR; PG8_MMA(1, 0, At, B0); PG8_MMA(1, 1, At, B1); PG8_BAR; PG8_SCHED;
;             PG8_LDB(B0, 1, 0); PG8_LDB(B1, 1, 1); PG8_SCHED; PG8_LDA(At, 1, 0); PG8_STAGE(PG8_SA(0, 1), a2 + hstep, voffA);
;             PG8_WAIT_V(8); PG8_WAIT_L(0); PG8_BAR; PG8_MMA(0, 0, At, B0); PG8_MMA(0, 1, At, B1); PG8_BAR; PG8_SCHED;
;             PG8_LDA(At, 1, 1); PG8_STAGE(PG8_SB(1, 0), b3, voffB); PG8_STAGE(PG8_SB(1, 1), b3 + hstep, voffB); PG8_STAGE(PG8_SA(1, 0), a3, voffA);
;             PG8_WAIT_V(8); PG8_WAIT_L(0); PG8_BAR; PG8_MMA(1, 0, At, B0); PG8_MMA(1, 1, At, B1); PG8_BAR; PG8_SCHED;
	v_mfma_f32_16x16x32_bf16 v[122:125], v[136:139], v[190:193], v[122:125]
	v_mfma_f32_16x16x32_bf16 v[86:89], v[144:147], v[190:193], v[86:89]
	v_mfma_f32_16x16x32_bf16 v[126:129], v[136:139], v[206:209], v[126:129]
	v_mfma_f32_16x16x32_bf16 v[82:85], v[144:147], v[206:209], v[82:85]
	v_mfma_f32_16x16x32_bf16 v[114:117], v[140:143], v[178:181], v[114:117]
	v_mfma_f32_16x16x32_bf16 v[94:97], v[148:151], v[178:181], v[94:97]
	v_mfma_f32_16x16x32_bf16 v[118:121], v[140:143], v[186:189], v[118:121]
	v_mfma_f32_16x16x32_bf16 v[90:93], v[148:151], v[186:189], v[90:93]
	v_mfma_f32_16x16x32_bf16 v[122:125], v[140:143], v[202:205], v[122:125]
	v_mfma_f32_16x16x32_bf16 v[86:89], v[148:151], v[202:205], v[86:89]
	v_mfma_f32_16x16x32_bf16 v[126:129], v[140:143], v[210:213], v[126:129]
	v_mfma_f32_16x16x32_bf16 v[82:85], v[148:151], v[210:213], v[82:85]
	s_setprio 0
	s_setprio 1
	v_mfma_f32_16x16x32_bf16 v[62:65], v[152:155], v[174:177], v[62:65]
	v_mfma_f32_16x16x32_bf16 v[18:21], v[160:163], v[174:177], v[18:21]
	v_mfma_f32_16x16x32_bf16 v[58:61], v[152:155], v[182:185], v[58:61]
	v_mfma_f32_16x16x32_bf16 v[22:25], v[160:163], v[182:185], v[22:25]
	v_mfma_f32_16x16x32_bf16 v[54:57], v[152:155], v[190:193], v[54:57]
	v_mfma_f32_16x16x32_bf16 v[26:29], v[160:163], v[190:193], v[26:29]
	v_mfma_f32_16x16x32_bf16 v[50:53], v[152:155], v[206:209], v[50:53]
	v_mfma_f32_16x16x32_bf16 v[30:33], v[160:163], v[206:209], v[30:33]
	v_mfma_f32_16x16x32_bf16 v[62:65], v[156:159], v[178:181], v[62:65]
	v_mfma_f32_16x16x32_bf16 v[18:21], v[164:167], v[178:181], v[18:21]
	v_mfma_f32_16x16x32_bf16 v[58:61], v[156:159], v[186:189], v[58:61]
	v_mfma_f32_16x16x32_bf16 v[22:25], v[164:167], v[186:189], v[22:25]
	v_mfma_f32_16x16x32_bf16 v[54:57], v[156:159], v[202:205], v[54:57]
	v_mfma_f32_16x16x32_bf16 v[26:29], v[164:167], v[202:205], v[26:29]
	v_mfma_f32_16x16x32_bf16 v[50:53], v[156:159], v[210:213], v[50:53]
	v_mfma_f32_16x16x32_bf16 v[30:33], v[164:167], v[210:213], v[30:33]
	s_setprio 0
	s_barrier
	s_add_i32 s64, 0, 0x18000
	s_add_i32 s65, 0, 0x1c000
	v_add_u32_e32 v148, s64, v171
	v_add_u32_e32 v164, s65, v171
	ds_read_b128 v[136:139], v148
	ds_read_b128 v[140:143], v148 offset:1024
	ds_read_b128 v[144:147], v148 offset:2048
	ds_read_b128 v[148:151], v148 offset:3072
	ds_read_b128 v[152:155], v164
	ds_read_b128 v[156:159], v164 offset:1024
	ds_read_b128 v[160:163], v164 offset:2048
	ds_read_b128 v[164:167], v164 offset:3072
	s_add_u32 s26, s42, 0x80000
	s_addc_u32 s27, s43, 0
	s_mov_b32 m0, s46
	v_lshl_add_u64 v[218:219], s[26:27], 0, v[0:1]
	v_add_u32_e32 v250, s101, v173
	ds_read_b128 v[174:177], v250
	ds_read_b128 v[178:181], v250 offset:1024
	ds_read_b128 v[182:185], v250 offset:2048
	ds_read_b128 v[186:189], v250 offset:3072
	ds_read_b128 v[190:193], v250 offset:4096
	ds_read_b128 v[202:205], v250 offset:5120
	ds_read_b128 v[206:209], v250 offset:6144
	ds_read_b128 v[210:213], v250 offset:7168
	global_load_lds_dwordx4 v[218:219], off
	v_lshl_add_u64 v[218:219], s[26:27], 0, v[130:131]
	s_mov_b32 m0, s47
	s_nop 0
	global_load_lds_dwordx4 v[218:219], off
	v_lshl_add_u64 v[242:243], v[238:239], 0, s[96:97]
	v_lshl_add_u64 v[244:245], v[240:241], 0, s[96:97]
	s_add_i32 m0, s100, s23
	s_nop 0
	global_load_lds_dwordx4 v[242:243], off
	s_add_i32 m0, m0, 0x2000
	s_nop 0
	global_load_lds_dwordx4 v[244:245], off
	s_waitcnt vmcnt(10)
	s_waitcnt lgkmcnt(0)
	s_setprio 1
	s_waitcnt lgkmcnt(0)
	v_mfma_f32_16x16x32_bf16 v[98:101], v[136:139], v[174:177], v[98:101]
	v_mfma_f32_16x16x32_bf16 v[78:81], v[144:147], v[174:177], v[78:81]
	v_mfma_f32_16x16x32_bf16 v[102:105], v[136:139], v[182:185], v[102:105]
	v_mfma_f32_16x16x32_bf16 v[74:77], v[144:147], v[182:185], v[74:77]
	s_barrier
; #define PG8_STAGE(bufoff, gbase, voff) do { _Pragma("unroll") for (int _i = 0; _i < 2; ++_i) \
;         __builtin_amdgcn_global_load_lds((const unsigned*)((const char*)(gbase) + (voff)[_i]), (PG8_LAS unsigned*)(lds + (bufoff) + ldsw + _i * 8192), 16, 0, 0); } while (0)
; #define PG8_LDA(dst, b, h) do { _Pragma("unroll") for (int m = 0; m < 4; ++m) _Pragma("unroll") for (int k = 0; k < 2; ++k) dst[m][k] = *(const PG8_LAS bf16x8*)(lds + PG8_SA(b, h) + aoff + m * 2048 + k * 1024); } while (0)
; #define PG8_LDB(dst, b, h) do { _Pragma("unroll") for (int n = 0; n < 2; ++n) _Pragma("unroll") for (int k = 0; k < 2; ++k) dst[n][k] = *(const PG8_LAS bf16x8*)(lds + PG8_SB(b, h) + boff + n * 2048 + k * 1024); } while (0)
; template <class Epi, class Sched, bool ALIGN_EPI = false, bool SP2 = false>
; __device__ __forceinline__ void gemm_phase(PG8_LAS unsigned char* lds, const Gemm g, const Sched& S, const Epi& E) {
;     ...
;         for (int t = 0; t < nt; t += 2) {
;             const bool last = (t == nt - 2);
;             const char* a1 = cA + (size_t)(t + 1) * kstep;
;             const char* a2 = last ? nA : cA + (size_t)(t + 2) * kstep; const char* b2 = last ? nB : cB + (size_t)(t + 2) * kstep;
;             const char* a3 = a2 + kstep; const char* b3 = b2 + kstep;
;             if (last && has_next) S.a_ready(nxt);
;             if constexpr (SP2) {
;             PG8_LDB(B0, 0, 0); PG8_LDB(B1, 0, 1); PG8_SCHED; PG8_LDA(At, 0, 0); PG8_STAGE(PG8_SA(1, 1), a1 + hstep, voffA);
;             PG8_WAIT_V(8); PG8_WAIT_L(0); PG8_BAR; PG8_MMA(0, 0, At, B0); PG8_MMA(0, 1, At, B1); PG8_BAR; PG8_SCHED;
;             PG8_LDA(At, 0, 1); PG8_STAGE(PG8_SB(0, 0), b2, voffB); PG8_STAGE(PG8_SB(0, 1), b2 + hstep, voffB); PG8_STAGE(PG8_SA(0, 0), a2, voffA);
;             PG8_WAIT_V(8); PG8_WAIT_L(0); PG8_BAR; PG8_MMA(1, 0, At, B0); PG8_MMA(1, 1, At, B1); PG8_BAR; PG8_SCHED;
;             PG8_LDB(B0, 1, 0); PG8_LDB(B1, 1, 1); PG8_SCHED; PG8_LDA(At, 1, 0); PG8_STAGE(PG8_SA(0, 1), a2 + hstep, voffA);
;             PG8_WAIT_V(8); PG8_WAIT_L(0); PG8_BAR; PG8_MMA(0, 0, At, B0); PG8_MMA(0, 1, At, B1); PG8_BAR; PG8_SCHED;
;             PG8_LDA(At, 1, 1); PG8_STAGE(PG8_SB(1, 0), b3, voffB); PG8_STAGE(PG8_SB(1, 1), b3 + hstep, voffB); PG8_STAGE(PG8_SA(1, 0), a3, voffA);
;             PG8_WAIT_V(8); PG8_WAIT_L(0); PG8_BAR; PG8_MMA(1, 0, At, B0); PG8_MMA(1, 1, At, B1); PG8_BAR; PG8_SCHED;
	v_mfma_f32_16x16x32_bf16 v[106:109], v[136:139], v[190:193], v[106:109]
	v_mfma_f32_16x16x32_bf16 v[70:73], v[144:147], v[190:193], v[70:73]
	v_mfma_f32_16x16x32_bf16 v[110:113], v[136:139], v[206:209], v[110:113]
	v_mfma_f32_16x16x32_bf16 v[66:69], v[144:147], v[206:209], v[66:69]
	v_mfma_f32_16x16x32_bf16 v[98:101], v[140:143], v[178:181], v[98:101]
	v_mfma_f32_16x16x32_bf16 v[78:81], v[148:151], v[178:181], v[78:81]
	v_mfma_f32_16x16x32_bf16 v[102:105], v[140:143], v[186:189], v[102:105]
	v_mfma_f32_16x16x32_bf16 v[74:77], v[148:151], v[186:189], v[74:77]
	v_mfma_f32_16x16x32_bf16 v[106:109], v[140:143], v[202:205], v[106:109]
	v_mfma_f32_16x16x32_bf16 v[70:73], v[148:151], v[202:205], v[70:73]
	v_mfma_f32_16x16x32_bf16 v[110:113], v[140:143], v[210:213], v[110:113]
	v_mfma_f32_16x16x32_bf16 v[66:69], v[148:151], v[210:213], v[66:69]
	s_setprio 0
	s_setprio 1
	v_mfma_f32_16x16x32_bf16 v[46:49], v[152:155], v[174:177], v[46:49]
	v_mfma_f32_16x16x32_bf16 v[2:5], v[160:163], v[174:177], v[2:5]
	v_mfma_f32_16x16x32_bf16 v[42:45], v[152:155], v[182:185], v[42:45]
	v_mfma_f32_16x16x32_bf16 v[6:9], v[160:163], v[182:185], v[6:9]
	v_mfma_f32_16x16x32_bf16 v[38:41], v[152:155], v[190:193], v[38:41]
	v_mfma_f32_16x16x32_bf16 v[10:13], v[160:163], v[190:193], v[10:13]
	v_mfma_f32_16x16x32_bf16 v[34:37], v[152:155], v[206:209], v[34:37]
	v_mfma_f32_16x16x32_bf16 v[14:17], v[160:163], v[206:209], v[14:17]
	v_mfma_f32_16x16x32_bf16 v[46:49], v[156:159], v[178:181], v[46:49]
	v_mfma_f32_16x16x32_bf16 v[2:5], v[164:167], v[178:181], v[2:5]
	v_mfma_f32_16x16x32_bf16 v[42:45], v[156:159], v[186:189], v[42:45]
	v_mfma_f32_16x16x32_bf16 v[6:9], v[164:167], v[186:189], v[6:9]
	v_mfma_f32_16x16x32_bf16 v[38:41], v[156:159], v[202:205], v[38:41]
	v_mfma_f32_16x16x32_bf16 v[10:13], v[164:167], v[202:205], v[10:13]
	v_mfma_f32_16x16x32_bf16 v[34:37], v[156:159], v[210:213], v[34:37]
	v_mfma_f32_16x16x32_bf16 v[14:17], v[164:167], v[210:213], v[14:17]
	s_setprio 0
	s_barrier
	s_add_i32 s26, s64, s44
	v_lshl_add_u64 v[168:169], v[168:169], 0, s[96:97]
	s_mov_b32 m0, s26
	ds_read_b128 v[174:177], v173 offset:49152
	ds_read_b128 v[178:181], v173 offset:50176
	ds_read_b128 v[182:185], v173 offset:51200
	ds_read_b128 v[186:189], v173 offset:52224
	ds_read_b128 v[190:193], v173 offset:53248
	ds_read_b128 v[202:205], v173 offset:54272
	ds_read_b128 v[206:209], v173 offset:55296
	ds_read_b128 v[210:213], v173 offset:56320
	global_load_lds_dwordx4 v[168:169], off
	s_add_i32 m0, s26, 0x2000
	s_add_u32 s26, s40, 0x80080
	v_lshl_add_u64 v[168:169], v[194:195], 0, s[96:97]
	s_addc_u32 s27, s41, 0
	s_add_i32 s40, s65, s44
	global_load_lds_dwordx4 v[168:169], off
	v_lshl_add_u64 v[168:169], s[26:27], 0, v[0:1]
	s_mov_b32 m0, s40
	s_nop 0
	global_load_lds_dwordx4 v[168:169], off
	v_lshl_add_u64 v[168:169], s[26:27], 0, v[130:131]
	s_add_i32 m0, s40, 0x2000
	s_nop 0
	global_load_lds_dwordx4 v[168:169], off
	s_waitcnt vmcnt(8)
	s_waitcnt lgkmcnt(0)
	s_setprio 1
	s_waitcnt lgkmcnt(0)
	v_mfma_f32_16x16x32_bf16 v[114:117], v[136:139], v[174:177], v[114:117]
	v_mfma_f32_16x16x32_bf16 v[94:97], v[144:147], v[174:177], v[94:97]
	v_mfma_f32_16x16x32_bf16 v[118:121], v[136:139], v[182:185], v[118:121]
	v_mfma_f32_16x16x32_bf16 v[90:93], v[144:147], v[182:185], v[90:93]
	s_barrier
	v_mfma_f32_16x16x32_bf16 v[122:125], v[136:139], v[190:193], v[122:125]
	v_mfma_f32_16x16x32_bf16 v[86:89], v[144:147], v[190:193], v[86:89]
	v_mfma_f32_16x16x32_bf16 v[126:129], v[136:139], v[206:209], v[126:129]
	v_mfma_f32_16x16x32_bf16 v[82:85], v[144:147], v[206:209], v[82:85]
	v_mfma_f32_16x16x32_bf16 v[114:117], v[140:143], v[178:181], v[114:117]
	v_mfma_f32_16x16x32_bf16 v[94:97], v[148:151], v[178:181], v[94:97]
	v_mfma_f32_16x16x32_bf16 v[118:121], v[140:143], v[186:189], v[118:121]
	v_mfma_f32_16x16x32_bf16 v[90:93], v[148:151], v[186:189], v[90:93]
	v_mfma_f32_16x16x32_bf16 v[122:125], v[140:143], v[202:205], v[122:125]
	v_mfma_f32_16x16x32_bf16 v[86:89], v[148:151], v[202:205], v[86:89]
	v_mfma_f32_16x16x32_bf16 v[126:129], v[140:143], v[210:213], v[126:129]
	v_mfma_f32_16x16x32_bf16 v[82:85], v[148:151], v[210:213], v[82:85]
	s_setprio 0
	s_setprio 1
	v_mfma_f32_16x16x32_bf16 v[62:65], v[152:155], v[174:177], v[62:65]
	v_mfma_f32_16x16x32_bf16 v[18:21], v[160:163], v[174:177], v[18:21]
	v_mfma_f32_16x16x32_bf16 v[58:61], v[152:155], v[182:185], v[58:61]
	v_mfma_f32_16x16x32_bf16 v[22:25], v[160:163], v[182:185], v[22:25]
	v_mfma_f32_16x16x32_bf16 v[54:57], v[152:155], v[190:193], v[54:57]
	v_mfma_f32_16x16x32_bf16 v[26:29], v[160:163], v[190:193], v[26:29]
	v_mfma_f32_16x16x32_bf16 v[50:53], v[152:155], v[206:209], v[50:53]
	v_mfma_f32_16x16x32_bf16 v[30:33], v[160:163], v[206:209], v[30:33]
	v_mfma_f32_16x16x32_bf16 v[62:65], v[156:159], v[178:181], v[62:65]
	v_mfma_f32_16x16x32_bf16 v[18:21], v[164:167], v[178:181], v[18:21]
	v_mfma_f32_16x16x32_bf16 v[58:61], v[156:159], v[186:189], v[58:61]
	v_mfma_f32_16x16x32_bf16 v[22:25], v[164:167], v[186:189], v[22:25]
	v_mfma_f32_16x16x32_bf16 v[54:57], v[156:159], v[202:205], v[54:57]
	v_mfma_f32_16x16x32_bf16 v[26:29], v[164:167], v[202:205], v[26:29]
	v_mfma_f32_16x16x32_bf16 v[50:53], v[156:159], v[210:213], v[50:53]
	v_mfma_f32_16x16x32_bf16 v[30:33], v[164:167], v[210:213], v[30:33]
	s_setprio 0
	s_barrier
	s_add_i32 s63, s63, 2
	s_mov_b32 s101, s100
	s_mov_b32 s100, vcc_hi
	s_add_u32 s61, s61, 0x100
	s_addc_u32 s62, s62, 0
	s_cmp_gt_u32 s63, 29
	s_mov_b64 s[26:27], s[38:39]
	s_cbranch_scc0 .LBB0_1255
	s_and_b64 vcc, exec, s[8:9]
	s_cbranch_vccz .LBB0_1258
	s_barrier

; #define PG8_STAGE(bufoff, gbase, voff) do { _Pragma("unroll") for (int _i = 0; _i < 2; ++_i) \
;         __builtin_amdgcn_global_load_lds((const unsigned*)((const char*)(gbase) + (voff)[_i]), (PG8_LAS unsigned*)(lds + (bufoff) + ldsw + _i * 8192), 16, 0, 0); } while (0)
; #define PG8_LDA(dst, b, h) do { _Pragma("unroll") for (int m = 0; m < 4; ++m) _Pragma("unroll") for (int k = 0; k < 2; ++k) dst[m][k] = *(const PG8_LAS bf16x8*)(lds + PG8_SA(b, h) + aoff + m * 2048 + k * 1024); } while (0)
; #define PG8_LDB(dst, b, h) do { _Pragma("unroll") for (int n = 0; n < 2; ++n) _Pragma("unroll") for (int k = 0; k < 2; ++k) dst[n][k] = *(const PG8_LAS bf16x8*)(lds + PG8_SB(b, h) + boff + n * 2048 + k * 1024); } while (0)
; template <class Epi, class Sched, bool ALIGN_EPI = false, bool SP2 = false>
; __device__ __forceinline__ void gemm_phase(PG8_LAS unsigned char* lds, const Gemm g, const Sched& S, const Epi& E) {
;     ...
;         for (int t = 0; t < nt; t += 2) {
;             const bool last = (t == nt - 2);
;             const char* a1 = cA + (size_t)(t + 1) * kstep;
;             const char* a2 = last ? nA : cA + (size_t)(t + 2) * kstep; const char* b2 = last ? nB : cB + (size_t)(t + 2) * kstep;
;             const char* a3 = a2 + kstep; const char* b3 = b2 + kstep;
;             if (last && has_next) S.a_ready(nxt);
;             if constexpr (SP2) {
;             PG8_LDB(B0, 0, 0); PG8_LDB(B1, 0, 1); PG8_SCHED; PG8_LDA(At, 0, 0); PG8_STAGE(PG8_SA(1, 1), a1 + hstep, voffA);
;             PG8_WAIT_V(8); PG8_WAIT_L(0); PG8_BAR; PG8_MMA(0, 0, At, B0); PG8_MMA(0, 1, At, B1); PG8_BAR; PG8_SCHED;
;             PG8_LDA(At, 0, 1); PG8_STAGE(PG8_SB(0, 0), b2, voffB); PG8_STAGE(PG8_SB(0, 1), b2 + hstep, voffB); PG8_STAGE(PG8_SA(0, 0), a2, voffA);
;             PG8_WAIT_V(8); PG8_WAIT_L(0); PG8_BAR; PG8_MMA(1, 0, At, B0); PG8_MMA(1, 1, At, B1); PG8_BAR; PG8_SCHED;
;             PG8_LDB(B0, 1, 0); PG8_LDB(B1, 1, 1); PG8_SCHED; PG8_LDA(At, 1, 0); PG8_STAGE(PG8_SA(0, 1), a2 + hstep, voffA);
;             PG8_WAIT_V(8); PG8_WAIT_L(0); PG8_BAR; PG8_MMA(0, 0, At, B0); PG8_MMA(0, 1, At, B1); PG8_BAR; PG8_SCHED;
;             PG8_LDA(At, 1, 1); PG8_STAGE(PG8_SB(1, 0), b3, voffB); PG8_STAGE(PG8_SB(1, 1), b3 + hstep, voffB); PG8_STAGE(PG8_SA(1, 0), a3, voffA);
;             PG8_WAIT_V(8); PG8_WAIT_L(0); PG8_BAR; PG8_MMA(1, 0, At, B0); PG8_MMA(1, 1, At, B1); PG8_BAR; PG8_SCHED;
.LBB0_1423:
	s_sub_i32 vcc_hi, 0x29000, s100
	s_sub_i32 vcc_hi, vcc_hi, s101
	s_add_u32 s61, s64, 0xfff80080
	s_addc_u32 s62, s65, -1
	s_add_i32 s85, 0, 0x10000
	s_cmp_eq_u32 s59, 28
	s_cselect_b32 s67, s0, s62
	s_cselect_b32 s66, s1, s61
	s_cselect_b32 s63, s28, s53
	s_cselect_b32 s62, s29, s51
	s_add_i32 s61, 0, 0x14000
	v_add_u32_e32 v142, s85, v169
	v_add_u32_e32 v158, s61, v169
	ds_read_b128 v[130:133], v142
	ds_read_b128 v[134:137], v142 offset:1024
	ds_read_b128 v[138:141], v142 offset:2048
	ds_read_b128 v[142:145], v142 offset:3072
	ds_read_b128 v[146:149], v158
	ds_read_b128 v[150:153], v158 offset:1024
	ds_read_b128 v[154:157], v158 offset:2048
	ds_read_b128 v[158:161], v158 offset:3072
	v_lshl_add_u64 v[202:203], s[64:65], 0, v[172:173]
	s_add_i32 m0, s77, 0xc000
	v_add_u32_e32 v250, s100, v208
	ds_read_b128 v[176:179], v250
	ds_read_b128 v[180:183], v250 offset:1024
	ds_read_b128 v[184:187], v250 offset:2048
	ds_read_b128 v[188:191], v250 offset:3072
	ds_read_b128 v[192:195], v250 offset:4096
	ds_read_b128 v[210:213], v250 offset:5120
	ds_read_b128 v[214:217], v250 offset:6144
	ds_read_b128 v[218:221], v250 offset:7168
	global_load_lds_dwordx4 v[202:203], off
	v_lshl_add_u64 v[202:203], s[64:65], 0, v[174:175]
	s_add_i32 m0, s77, 0xe000
	s_nop 0
	global_load_lds_dwordx4 v[202:203], off
	v_lshl_add_u64 v[244:245], s[66:67], 0, v[162:163]
	v_lshl_add_u64 v[246:247], s[66:67], 0, v[164:165]
	s_add_i32 m0, vcc_hi, s77
	s_nop 0
	global_load_lds_dwordx4 v[244:245], off
	s_add_i32 m0, m0, 0x2000
	s_nop 0
	global_load_lds_dwordx4 v[246:247], off
	s_waitcnt vmcnt(10)
	s_waitcnt lgkmcnt(0)
	s_setprio 1
	s_waitcnt lgkmcnt(0)
	v_mfma_f32_16x16x32_bf16 v[122:125], v[130:133], v[176:179], v[122:125]
	v_mfma_f32_16x16x32_bf16 v[58:61], v[138:141], v[176:179], v[58:61]
	v_mfma_f32_16x16x32_bf16 v[114:117], v[130:133], v[184:187], v[114:117]
	v_mfma_f32_16x16x32_bf16 v[50:53], v[138:141], v[184:187], v[50:53]
	s_barrier
	v_mfma_f32_16x16x32_bf16 v[106:109], v[130:133], v[192:195], v[106:109]
	v_mfma_f32_16x16x32_bf16 v[42:45], v[138:141], v[192:195], v[42:45]
	v_mfma_f32_16x16x32_bf16 v[98:101], v[130:133], v[214:217], v[98:101]
	v_mfma_f32_16x16x32_bf16 v[34:37], v[138:141], v[214:217], v[34:37]
	v_mfma_f32_16x16x32_bf16 v[122:125], v[134:137], v[180:183], v[122:125]
	v_mfma_f32_16x16x32_bf16 v[58:61], v[142:145], v[180:183], v[58:61]
	v_mfma_f32_16x16x32_bf16 v[114:117], v[134:137], v[188:191], v[114:117]
	v_mfma_f32_16x16x32_bf16 v[50:53], v[142:145], v[188:191], v[50:53]
	v_mfma_f32_16x16x32_bf16 v[106:109], v[134:137], v[210:213], v[106:109]
	v_mfma_f32_16x16x32_bf16 v[42:45], v[142:145], v[210:213], v[42:45]
	v_mfma_f32_16x16x32_bf16 v[98:101], v[134:137], v[218:221], v[98:101]
	v_mfma_f32_16x16x32_bf16 v[34:37], v[142:145], v[218:221], v[34:37]
	s_setprio 0
	s_setprio 1
	v_mfma_f32_16x16x32_bf16 v[126:129], v[146:149], v[176:179], v[126:129]
	v_mfma_f32_16x16x32_bf16 v[62:65], v[154:157], v[176:179], v[62:65]
	v_mfma_f32_16x16x32_bf16 v[118:121], v[146:149], v[184:187], v[118:121]
	v_mfma_f32_16x16x32_bf16 v[54:57], v[154:157], v[184:187], v[54:57]
	v_mfma_f32_16x16x32_bf16 v[110:113], v[146:149], v[192:195], v[110:113]
	v_mfma_f32_16x16x32_bf16 v[46:49], v[154:157], v[192:195], v[46:49]
	v_mfma_f32_16x16x32_bf16 v[102:105], v[146:149], v[214:217], v[102:105]
	v_mfma_f32_16x16x32_bf16 v[38:41], v[154:157], v[214:217], v[38:41]
	v_mfma_f32_16x16x32_bf16 v[126:129], v[150:153], v[180:183], v[126:129]
	v_mfma_f32_16x16x32_bf16 v[62:65], v[158:161], v[180:183], v[62:65]
	v_mfma_f32_16x16x32_bf16 v[118:121], v[150:153], v[188:191], v[118:121]
	v_mfma_f32_16x16x32_bf16 v[54:57], v[158:161], v[188:191], v[54:57]
	v_mfma_f32_16x16x32_bf16 v[110:113], v[150:153], v[210:213], v[110:113]
	v_mfma_f32_16x16x32_bf16 v[46:49], v[158:161], v[210:213], v[46:49]
	v_mfma_f32_16x16x32_bf16 v[102:105], v[150:153], v[218:221], v[102:105]
	v_mfma_f32_16x16x32_bf16 v[38:41], v[158:161], v[218:221], v[38:41]
	s_setprio 0
	s_barrier
	s_add_i32 s85, s85, s76
	v_lshl_add_u64 v[202:203], s[62:63], 0, v[0:1]
	s_mov_b32 m0, s85
	ds_read_b128 v[176:179], v208 offset:16384
	ds_read_b128 v[180:183], v208 offset:17408
	ds_read_b128 v[184:187], v208 offset:18432
	ds_read_b128 v[188:191], v208 offset:19456
	ds_read_b128 v[192:195], v208 offset:20480
	ds_read_b128 v[210:213], v208 offset:21504
	ds_read_b128 v[214:217], v208 offset:22528
	ds_read_b128 v[218:221], v208 offset:23552
	global_load_lds_dwordx4 v[202:203], off
	s_add_i32 m0, s85, 0x2000
	s_add_u32 s86, s62, 0x80000
	v_lshl_add_u64 v[230:231], s[62:63], 0, v[166:167]
	s_addc_u32 s87, s63, 0
	s_add_i32 s61, s61, s76
	global_load_lds_dwordx4 v[230:231], off
	v_lshl_add_u64 v[238:239], s[86:87], 0, v[0:1]
	s_mov_b32 m0, s61
	s_nop 0
	global_load_lds_dwordx4 v[238:239], off
	v_lshl_add_u64 v[238:239], s[86:87], 0, v[166:167]
	s_add_i32 m0, s61, 0x2000
	s_nop 0
	global_load_lds_dwordx4 v[238:239], off
	s_waitcnt vmcnt(8)
	s_waitcnt lgkmcnt(0)
	s_setprio 1
	s_waitcnt lgkmcnt(0)
	v_mfma_f32_16x16x32_bf16 v[90:93], v[130:133], v[176:179], v[90:93]
	v_mfma_f32_16x16x32_bf16 v[26:29], v[138:141], v[176:179], v[26:29]
	v_mfma_f32_16x16x32_bf16 v[82:85], v[130:133], v[184:187], v[82:85]
	v_mfma_f32_16x16x32_bf16 v[18:21], v[138:141], v[184:187], v[18:21]
	s_barrier
; #define PG8_STAGE(bufoff, gbase, voff) do { _Pragma("unroll") for (int _i = 0; _i < 2; ++_i) \
;         __builtin_amdgcn_global_load_lds((const unsigned*)((const char*)(gbase) + (voff)[_i]), (PG8_LAS unsigned*)(lds + (bufoff) + ldsw + _i * 8192), 16, 0, 0); } while (0)
; #define PG8_LDA(dst, b, h) do { _Pragma("unroll") for (int m = 0; m < 4; ++m) _Pragma("unroll") for (int k = 0; k < 2; ++k) dst[m][k] = *(const PG8_LAS bf16x8*)(lds + PG8_SA(b, h) + aoff + m * 2048 + k * 1024); } while (0)
; #define PG8_LDB(dst, b, h) do { _Pragma("unroll") for (int n = 0; n < 2; ++n) _Pragma("unroll") for (int k = 0; k < 2; ++k) dst[n][k] = *(const PG8_LAS bf16x8*)(lds + PG8_SB(b, h) + boff + n * 2048 + k * 1024); } while (0)
; template <class Epi, class Sched, bool ALIGN_EPI = false, bool SP2 = false>
; __device__ __forceinline__ void gemm_phase(PG8_LAS unsigned char* lds, const Gemm g, const Sched& S, const Epi& E) {
;     ...
;         for (int t = 0; t < nt; t += 2) {
;             const bool last = (t == nt - 2);
;             const char* a1 = cA + (size_t)(t + 1) * kstep;
;             const char* a2 = last ? nA : cA + (size_t)(t + 2) * kstep; const char* b2 = last ? nB : cB + (size_t)(t + 2) * kstep;
;             const char* a3 = a2 + kstep; const char* b3 = b2 + kstep;
;             if (last && has_next) S.a_ready(nxt);
;             if constexpr (SP2) {
;             PG8_LDB(B0, 0, 0); PG8_LDB(B1, 0, 1); PG8_SCHED; PG8_LDA(At, 0, 0); PG8_STAGE(PG8_SA(1, 1), a1 + hstep, voffA);
;             PG8_WAIT_V(8); PG8_WAIT_L(0); PG8_BAR; PG8_MMA(0, 0, At, B0); PG8_MMA(0, 1, At, B1); PG8_BAR; PG8_SCHED;
;             PG8_LDA(At, 0, 1); PG8_STAGE(PG8_SB(0, 0), b2, voffB); PG8_STAGE(PG8_SB(0, 1), b2 + hstep, voffB); PG8_STAGE(PG8_SA(0, 0), a2, voffA);
;             PG8_WAIT_V(8); PG8_WAIT_L(0); PG8_BAR; PG8_MMA(1, 0, At, B0); PG8_MMA(1, 1, At, B1); PG8_BAR; PG8_SCHED;
;             PG8_LDB(B0, 1, 0); PG8_LDB(B1, 1, 1); PG8_SCHED; PG8_LDA(At, 1, 0); PG8_STAGE(PG8_SA(0, 1), a2 + hstep, voffA);
;             PG8_WAIT_V(8); PG8_WAIT_L(0); PG8_BAR; PG8_MMA(0, 0, At, B0); PG8_MMA(0, 1, At, B1); PG8_BAR; PG8_SCHED;
;             PG8_LDA(At, 1, 1); PG8_STAGE(PG8_SB(1, 0), b3, voffB); PG8_STAGE(PG8_SB(1, 1), b3 + hstep, voffB); PG8_STAGE(PG8_SA(1, 0), a3, voffA);
;             PG8_WAIT_V(8); PG8_WAIT_L(0); PG8_BAR; PG8_MMA(1, 0, At, B0); PG8_MMA(1, 1, At, B1); PG8_BAR; PG8_SCHED;
	v_mfma_f32_16x16x32_bf16 v[74:77], v[130:133], v[192:195], v[74:77]
	v_mfma_f32_16x16x32_bf16 v[10:13], v[138:141], v[192:195], v[10:13]
	v_mfma_f32_16x16x32_bf16 v[66:69], v[130:133], v[214:217], v[66:69]
	v_mfma_f32_16x16x32_bf16 v[2:5], v[138:141], v[214:217], v[2:5]
	v_mfma_f32_16x16x32_bf16 v[90:93], v[134:137], v[180:183], v[90:93]
	v_mfma_f32_16x16x32_bf16 v[26:29], v[142:145], v[180:183], v[26:29]
	v_mfma_f32_16x16x32_bf16 v[82:85], v[134:137], v[188:191], v[82:85]
	v_mfma_f32_16x16x32_bf16 v[18:21], v[142:145], v[188:191], v[18:21]
	v_mfma_f32_16x16x32_bf16 v[74:77], v[134:137], v[210:213], v[74:77]
	v_mfma_f32_16x16x32_bf16 v[10:13], v[142:145], v[210:213], v[10:13]
	v_mfma_f32_16x16x32_bf16 v[66:69], v[134:137], v[218:221], v[66:69]
	v_mfma_f32_16x16x32_bf16 v[2:5], v[142:145], v[218:221], v[2:5]
	s_setprio 0
	s_setprio 1
	v_mfma_f32_16x16x32_bf16 v[94:97], v[146:149], v[176:179], v[94:97]
	v_mfma_f32_16x16x32_bf16 v[30:33], v[154:157], v[176:179], v[30:33]
	v_mfma_f32_16x16x32_bf16 v[86:89], v[146:149], v[184:187], v[86:89]
	v_mfma_f32_16x16x32_bf16 v[22:25], v[154:157], v[184:187], v[22:25]
	v_mfma_f32_16x16x32_bf16 v[78:81], v[146:149], v[192:195], v[78:81]
	v_mfma_f32_16x16x32_bf16 v[14:17], v[154:157], v[192:195], v[14:17]
	v_mfma_f32_16x16x32_bf16 v[70:73], v[146:149], v[214:217], v[70:73]
	v_mfma_f32_16x16x32_bf16 v[6:9], v[154:157], v[214:217], v[6:9]
	v_mfma_f32_16x16x32_bf16 v[94:97], v[150:153], v[180:183], v[94:97]
	v_mfma_f32_16x16x32_bf16 v[30:33], v[158:161], v[180:183], v[30:33]
	v_mfma_f32_16x16x32_bf16 v[86:89], v[150:153], v[188:191], v[86:89]
	v_mfma_f32_16x16x32_bf16 v[22:25], v[158:161], v[188:191], v[22:25]
	v_mfma_f32_16x16x32_bf16 v[78:81], v[150:153], v[210:213], v[78:81]
	v_mfma_f32_16x16x32_bf16 v[14:17], v[158:161], v[210:213], v[14:17]
	v_mfma_f32_16x16x32_bf16 v[70:73], v[150:153], v[218:221], v[70:73]
	v_mfma_f32_16x16x32_bf16 v[6:9], v[158:161], v[218:221], v[6:9]
	s_setprio 0
	s_barrier
	s_add_i32 s61, 0, 0x18000
	s_add_i32 s85, 0, 0x1c000
	v_add_u32_e32 v142, s61, v169
	v_add_u32_e32 v158, s85, v169
	ds_read_b128 v[130:133], v142
	ds_read_b128 v[134:137], v142 offset:1024
	ds_read_b128 v[138:141], v142 offset:2048
	ds_read_b128 v[142:145], v142 offset:3072
	ds_read_b128 v[146:149], v158
	ds_read_b128 v[150:153], v158 offset:1024
	ds_read_b128 v[154:157], v158 offset:2048
	ds_read_b128 v[158:161], v158 offset:3072
	s_add_u32 s66, s66, 0x80000
	s_addc_u32 s67, s67, 0
	s_mov_b32 m0, s79
	v_lshl_add_u64 v[242:243], s[66:67], 0, v[162:163]
	v_add_u32_e32 v250, s101, v208
	ds_read_b128 v[176:179], v250
	ds_read_b128 v[180:183], v250 offset:1024
	ds_read_b128 v[184:187], v250 offset:2048
	ds_read_b128 v[188:191], v250 offset:3072
	ds_read_b128 v[192:195], v250 offset:4096
	ds_read_b128 v[210:213], v250 offset:5120
	ds_read_b128 v[214:217], v250 offset:6144
	ds_read_b128 v[218:221], v250 offset:7168
	global_load_lds_dwordx4 v[242:243], off
	v_lshl_add_u64 v[242:243], s[66:67], 0, v[164:165]
	s_mov_b32 m0, s80
	s_nop 0
	global_load_lds_dwordx4 v[242:243], off
	v_lshl_add_u64 v[248:249], v[244:245], 0, s[96:97]
	v_lshl_add_u64 v[242:243], v[246:247], 0, s[96:97]
	s_add_i32 m0, s100, s77
	s_nop 0
	global_load_lds_dwordx4 v[248:249], off
	s_add_i32 m0, m0, 0x2000
	s_nop 0
	global_load_lds_dwordx4 v[242:243], off
	s_waitcnt vmcnt(10)
	s_waitcnt lgkmcnt(0)
	s_setprio 1
	s_waitcnt lgkmcnt(0)
	v_mfma_f32_16x16x32_bf16 v[122:125], v[130:133], v[176:179], v[122:125]
	v_mfma_f32_16x16x32_bf16 v[58:61], v[138:141], v[176:179], v[58:61]
	v_mfma_f32_16x16x32_bf16 v[114:117], v[130:133], v[184:187], v[114:117]
	v_mfma_f32_16x16x32_bf16 v[50:53], v[138:141], v[184:187], v[50:53]
	s_barrier
; #define PG8_STAGE(bufoff, gbase, voff) do { _Pragma("unroll") for (int _i = 0; _i < 2; ++_i) \
;         __builtin_amdgcn_global_load_lds((const unsigned*)((const char*)(gbase) + (voff)[_i]), (PG8_LAS unsigned*)(lds + (bufoff) + ldsw + _i * 8192), 16, 0, 0); } while (0)
; #define PG8_LDA(dst, b, h) do { _Pragma("unroll") for (int m = 0; m < 4; ++m) _Pragma("unroll") for (int k = 0; k < 2; ++k) dst[m][k] = *(const PG8_LAS bf16x8*)(lds + PG8_SA(b, h) + aoff + m * 2048 + k * 1024); } while (0)
; #define PG8_LDB(dst, b, h) do { _Pragma("unroll") for (int n = 0; n < 2; ++n) _Pragma("unroll") for (int k = 0; k < 2; ++k) dst[n][k] = *(const PG8_LAS bf16x8*)(lds + PG8_SB(b, h) + boff + n * 2048 + k * 1024); } while (0)
; template <class Epi, class Sched, bool ALIGN_EPI = false, bool SP2 = false>
; __device__ __forceinline__ void gemm_phase(PG8_LAS unsigned char* lds, const Gemm g, const Sched& S, const Epi& E) {
;     ...
;         for (int t = 0; t < nt; t += 2) {
;             const bool last = (t == nt - 2);
;             const char* a1 = cA + (size_t)(t + 1) * kstep;
;             const char* a2 = last ? nA : cA + (size_t)(t + 2) * kstep; const char* b2 = last ? nB : cB + (size_t)(t + 2) * kstep;
;             const char* a3 = a2 + kstep; const char* b3 = b2 + kstep;
;             if (last && has_next) S.a_ready(nxt);
;             if constexpr (SP2) {
;             PG8_LDB(B0, 0, 0); PG8_LDB(B1, 0, 1); PG8_SCHED; PG8_LDA(At, 0, 0); PG8_STAGE(PG8_SA(1, 1), a1 + hstep, voffA);
;             PG8_WAIT_V(8); PG8_WAIT_L(0); PG8_BAR; PG8_MMA(0, 0, At, B0); PG8_MMA(0, 1, At, B1); PG8_BAR; PG8_SCHED;
;             PG8_LDA(At, 0, 1); PG8_STAGE(PG8_SB(0, 0), b2, voffB); PG8_STAGE(PG8_SB(0, 1), b2 + hstep, voffB); PG8_STAGE(PG8_SA(0, 0), a2, voffA);
;             PG8_WAIT_V(8); PG8_WAIT_L(0); PG8_BAR; PG8_MMA(1, 0, At, B0); PG8_MMA(1, 1, At, B1); PG8_BAR; PG8_SCHED;
;             PG8_LDB(B0, 1, 0); PG8_LDB(B1, 1, 1); PG8_SCHED; PG8_LDA(At, 1, 0); PG8_STAGE(PG8_SA(0, 1), a2 + hstep, voffA);
;             PG8_WAIT_V(8); PG8_WAIT_L(0); PG8_BAR; PG8_MMA(0, 0, At, B0); PG8_MMA(0, 1, At, B1); PG8_BAR; PG8_SCHED;
;             PG8_LDA(At, 1, 1); PG8_STAGE(PG8_SB(1, 0), b3, voffB); PG8_STAGE(PG8_SB(1, 1), b3 + hstep, voffB); PG8_STAGE(PG8_SA(1, 0), a3, voffA);
;             PG8_WAIT_V(8); PG8_WAIT_L(0); PG8_BAR; PG8_MMA(1, 0, At, B0); PG8_MMA(1, 1, At, B1); PG8_BAR; PG8_SCHED;
	v_mfma_f32_16x16x32_bf16 v[106:109], v[130:133], v[192:195], v[106:109]
	v_mfma_f32_16x16x32_bf16 v[42:45], v[138:141], v[192:195], v[42:45]
	v_mfma_f32_16x16x32_bf16 v[98:101], v[130:133], v[214:217], v[98:101]
	v_mfma_f32_16x16x32_bf16 v[34:37], v[138:141], v[214:217], v[34:37]
	v_mfma_f32_16x16x32_bf16 v[122:125], v[134:137], v[180:183], v[122:125]
	v_mfma_f32_16x16x32_bf16 v[58:61], v[142:145], v[180:183], v[58:61]
	v_mfma_f32_16x16x32_bf16 v[114:117], v[134:137], v[188:191], v[114:117]
	v_mfma_f32_16x16x32_bf16 v[50:53], v[142:145], v[188:191], v[50:53]
	v_mfma_f32_16x16x32_bf16 v[106:109], v[134:137], v[210:213], v[106:109]
	v_mfma_f32_16x16x32_bf16 v[42:45], v[142:145], v[210:213], v[42:45]
	v_mfma_f32_16x16x32_bf16 v[98:101], v[134:137], v[218:221], v[98:101]
	v_mfma_f32_16x16x32_bf16 v[34:37], v[142:145], v[218:221], v[34:37]
	s_setprio 0
	s_setprio 1
	v_mfma_f32_16x16x32_bf16 v[126:129], v[146:149], v[176:179], v[126:129]
	v_mfma_f32_16x16x32_bf16 v[62:65], v[154:157], v[176:179], v[62:65]
	v_mfma_f32_16x16x32_bf16 v[118:121], v[146:149], v[184:187], v[118:121]
	v_mfma_f32_16x16x32_bf16 v[54:57], v[154:157], v[184:187], v[54:57]
	v_mfma_f32_16x16x32_bf16 v[110:113], v[146:149], v[192:195], v[110:113]
	v_mfma_f32_16x16x32_bf16 v[46:49], v[154:157], v[192:195], v[46:49]
	v_mfma_f32_16x16x32_bf16 v[102:105], v[146:149], v[214:217], v[102:105]
	v_mfma_f32_16x16x32_bf16 v[38:41], v[154:157], v[214:217], v[38:41]
	v_mfma_f32_16x16x32_bf16 v[126:129], v[150:153], v[180:183], v[126:129]
	v_mfma_f32_16x16x32_bf16 v[62:65], v[158:161], v[180:183], v[62:65]
	v_mfma_f32_16x16x32_bf16 v[118:121], v[150:153], v[188:191], v[118:121]
	v_mfma_f32_16x16x32_bf16 v[54:57], v[158:161], v[188:191], v[54:57]
	v_mfma_f32_16x16x32_bf16 v[110:113], v[150:153], v[210:213], v[110:113]
	v_mfma_f32_16x16x32_bf16 v[46:49], v[158:161], v[210:213], v[46:49]
	v_mfma_f32_16x16x32_bf16 v[102:105], v[150:153], v[218:221], v[102:105]
	v_mfma_f32_16x16x32_bf16 v[38:41], v[158:161], v[218:221], v[38:41]
	s_setprio 0
	s_barrier
	s_add_i32 s61, s61, s76
	v_lshl_add_u64 v[202:203], v[202:203], 0, s[96:97]
	s_mov_b32 m0, s61
	ds_read_b128 v[176:179], v208 offset:49152
	ds_read_b128 v[180:183], v208 offset:50176
	ds_read_b128 v[184:187], v208 offset:51200
	ds_read_b128 v[188:191], v208 offset:52224
	ds_read_b128 v[192:195], v208 offset:53248
	ds_read_b128 v[210:213], v208 offset:54272
	ds_read_b128 v[214:217], v208 offset:55296
	ds_read_b128 v[218:221], v208 offset:56320
	global_load_lds_dwordx4 v[202:203], off
	s_add_i32 m0, s61, 0x2000
	s_add_u32 s62, s62, 0x80080
	v_lshl_add_u64 v[202:203], v[230:231], 0, s[96:97]
	s_addc_u32 s63, s63, 0
	s_add_i32 s61, s85, s76
	global_load_lds_dwordx4 v[202:203], off
	v_lshl_add_u64 v[202:203], s[62:63], 0, v[0:1]
	s_mov_b32 m0, s61
	s_nop 0
	global_load_lds_dwordx4 v[202:203], off
	v_lshl_add_u64 v[202:203], s[62:63], 0, v[166:167]
	s_add_i32 m0, s61, 0x2000
	s_nop 0
	global_load_lds_dwordx4 v[202:203], off
	s_waitcnt vmcnt(8)
	s_waitcnt lgkmcnt(0)
	s_setprio 1
	s_waitcnt lgkmcnt(0)
	v_mfma_f32_16x16x32_bf16 v[90:93], v[130:133], v[176:179], v[90:93]
	v_mfma_f32_16x16x32_bf16 v[26:29], v[138:141], v[176:179], v[26:29]
	v_mfma_f32_16x16x32_bf16 v[82:85], v[130:133], v[184:187], v[82:85]
	v_mfma_f32_16x16x32_bf16 v[18:21], v[138:141], v[184:187], v[18:21]
	s_barrier
	v_mfma_f32_16x16x32_bf16 v[74:77], v[130:133], v[192:195], v[74:77]
	v_mfma_f32_16x16x32_bf16 v[10:13], v[138:141], v[192:195], v[10:13]
	v_mfma_f32_16x16x32_bf16 v[66:69], v[130:133], v[214:217], v[66:69]
	v_mfma_f32_16x16x32_bf16 v[2:5], v[138:141], v[214:217], v[2:5]
	v_mfma_f32_16x16x32_bf16 v[90:93], v[134:137], v[180:183], v[90:93]
	v_mfma_f32_16x16x32_bf16 v[26:29], v[142:145], v[180:183], v[26:29]
	v_mfma_f32_16x16x32_bf16 v[82:85], v[134:137], v[188:191], v[82:85]
	v_mfma_f32_16x16x32_bf16 v[18:21], v[142:145], v[188:191], v[18:21]
	v_mfma_f32_16x16x32_bf16 v[74:77], v[134:137], v[210:213], v[74:77]
	v_mfma_f32_16x16x32_bf16 v[10:13], v[142:145], v[210:213], v[10:13]
	v_mfma_f32_16x16x32_bf16 v[66:69], v[134:137], v[218:221], v[66:69]
	v_mfma_f32_16x16x32_bf16 v[2:5], v[142:145], v[218:221], v[2:5]
	s_setprio 0
	s_setprio 1
	v_mfma_f32_16x16x32_bf16 v[94:97], v[146:149], v[176:179], v[94:97]
	v_mfma_f32_16x16x32_bf16 v[30:33], v[154:157], v[176:179], v[30:33]
	v_mfma_f32_16x16x32_bf16 v[86:89], v[146:149], v[184:187], v[86:89]
	v_mfma_f32_16x16x32_bf16 v[22:25], v[154:157], v[184:187], v[22:25]
	v_mfma_f32_16x16x32_bf16 v[78:81], v[146:149], v[192:195], v[78:81]
	v_mfma_f32_16x16x32_bf16 v[14:17], v[154:157], v[192:195], v[14:17]
	v_mfma_f32_16x16x32_bf16 v[70:73], v[146:149], v[214:217], v[70:73]
	v_mfma_f32_16x16x32_bf16 v[6:9], v[154:157], v[214:217], v[6:9]
	v_mfma_f32_16x16x32_bf16 v[94:97], v[150:153], v[180:183], v[94:97]
	v_mfma_f32_16x16x32_bf16 v[30:33], v[158:161], v[180:183], v[30:33]
	v_mfma_f32_16x16x32_bf16 v[86:89], v[150:153], v[188:191], v[86:89]
	v_mfma_f32_16x16x32_bf16 v[22:25], v[158:161], v[188:191], v[22:25]
	v_mfma_f32_16x16x32_bf16 v[78:81], v[150:153], v[210:213], v[78:81]
	v_mfma_f32_16x16x32_bf16 v[14:17], v[158:161], v[210:213], v[14:17]
	v_mfma_f32_16x16x32_bf16 v[70:73], v[150:153], v[218:221], v[70:73]
	v_mfma_f32_16x16x32_bf16 v[6:9], v[158:161], v[218:221], v[6:9]
	s_setprio 0
	s_barrier
	s_add_i32 s59, s59, 2
	s_mov_b32 s101, s100
	s_mov_b32 s100, vcc_hi
	s_add_u32 s64, s64, 0x100
	s_addc_u32 s65, s65, 0
	s_add_u32 s51, s51, 0x100
	s_addc_u32 s53, s53, 0
	s_cmp_gt_u32 s59, 29
	s_cbranch_scc0 .LBB0_1423
	s_and_b64 vcc, exec, s[48:49]
	s_cbranch_vccz .LBB0_1426
	s_barrier

; #define PG8_STAGE(bufoff, gbase, voff) do { _Pragma("unroll") for (int _i = 0; _i < 2; ++_i) \
;         __builtin_amdgcn_global_load_lds((const unsigned*)((const char*)(gbase) + (voff)[_i]), (PG8_LAS unsigned*)(lds + (bufoff) + ldsw + _i * 8192), 16, 0, 0); } while (0)
; #define PG8_LDA(dst, b, h) do { _Pragma("unroll") for (int m = 0; m < 4; ++m) _Pragma("unroll") for (int k = 0; k < 2; ++k) dst[m][k] = *(const PG8_LAS bf16x8*)(lds + PG8_SA(b, h) + aoff + m * 2048 + k * 1024); } while (0)
; #define PG8_LDB(dst, b, h) do { _Pragma("unroll") for (int n = 0; n < 2; ++n) _Pragma("unroll") for (int k = 0; k < 2; ++k) dst[n][k] = *(const PG8_LAS bf16x8*)(lds + PG8_SB(b, h) + boff + n * 2048 + k * 1024); } while (0)
; template <class Epi, class Sched, bool ALIGN_EPI = false, bool SP2 = false>
; __device__ __forceinline__ void gemm_phase(PG8_LAS unsigned char* lds, const Gemm g, const Sched& S, const Epi& E) {
;     ...
;         for (int t = 0; t < nt; t += 2) {
;             const bool last = (t == nt - 2);
;             const char* a1 = cA + (size_t)(t + 1) * kstep;
;             const char* a2 = last ? nA : cA + (size_t)(t + 2) * kstep; const char* b2 = last ? nB : cB + (size_t)(t + 2) * kstep;
;             const char* a3 = a2 + kstep; const char* b3 = b2 + kstep;
;             if (last && has_next) S.a_ready(nxt);
;             if constexpr (SP2) {
;             PG8_LDB(B0, 0, 0); PG8_LDB(B1, 0, 1); PG8_SCHED; PG8_LDA(At, 0, 0); PG8_STAGE(PG8_SA(1, 1), a1 + hstep, voffA);
;             PG8_WAIT_V(8); PG8_WAIT_L(0); PG8_BAR; PG8_MMA(0, 0, At, B0); PG8_MMA(0, 1, At, B1); PG8_BAR; PG8_SCHED;
;             PG8_LDA(At, 0, 1); PG8_STAGE(PG8_SB(0, 0), b2, voffB); PG8_STAGE(PG8_SB(0, 1), b2 + hstep, voffB); PG8_STAGE(PG8_SA(0, 0), a2, voffA);
;             PG8_WAIT_V(8); PG8_WAIT_L(0); PG8_BAR; PG8_MMA(1, 0, At, B0); PG8_MMA(1, 1, At, B1); PG8_BAR; PG8_SCHED;
;             PG8_LDB(B0, 1, 0); PG8_LDB(B1, 1, 1); PG8_SCHED; PG8_LDA(At, 1, 0); PG8_STAGE(PG8_SA(0, 1), a2 + hstep, voffA);
;             PG8_WAIT_V(8); PG8_WAIT_L(0); PG8_BAR; PG8_MMA(0, 0, At, B0); PG8_MMA(0, 1, At, B1); PG8_BAR; PG8_SCHED;
;             PG8_LDA(At, 1, 1); PG8_STAGE(PG8_SB(1, 0), b3, voffB); PG8_STAGE(PG8_SB(1, 1), b3 + hstep, voffB); PG8_STAGE(PG8_SA(1, 0), a3, voffA);
;             PG8_WAIT_V(8); PG8_WAIT_L(0); PG8_BAR; PG8_MMA(1, 0, At, B0); PG8_MMA(1, 1, At, B1); PG8_BAR; PG8_SCHED;
.LBB0_1593:
	s_sub_i32 vcc_hi, 0x29000, s100
	s_sub_i32 vcc_hi, vcc_hi, s101
	s_add_u32 s40, s38, 0x100
	s_addc_u32 s41, s39, 0
	s_add_i32 s65, 0, 0x10000
	s_cmpk_eq_i32 s64, 0x54
	s_cselect_b32 s45, s7, s41
	s_cselect_b32 s44, s6, s40
	v_add_u32_e32 v144, s65, v147
	s_cselect_b32 s43, s27, s63
	s_cselect_b32 s42, s26, s62
	s_add_i32 s66, 0, 0x14000
	ds_read_b128 v[136:139], v144
	ds_read_b128 v[140:143], v144 offset:1024
	ds_read_b128 v[150:153], v144 offset:2048
	ds_read_b128 v[154:157], v144 offset:3072
	v_add_u32_e32 v144, s66, v147
	ds_read_b128 v[158:161], v144
	ds_read_b128 v[162:165], v144 offset:1024
	ds_read_b128 v[166:169], v144 offset:2048
	ds_read_b128 v[170:173], v144 offset:3072
	v_lshl_add_u64 v[144:145], s[38:39], 0, v[132:133]
	s_add_i32 m0, s47, 0xc000
	v_add_u32_e32 v250, s100, v149
	ds_read_b128 v[174:177], v250
	ds_read_b128 v[178:181], v250 offset:1024
	ds_read_b128 v[182:185], v250 offset:2048
	ds_read_b128 v[186:189], v250 offset:3072
	ds_read_b128 v[190:193], v250 offset:4096
	ds_read_b128 v[202:205], v250 offset:5120
	ds_read_b128 v[206:209], v250 offset:6144
	ds_read_b128 v[210:213], v250 offset:7168
	global_load_lds_dwordx4 v[144:145], off
	v_lshl_add_u64 v[144:145], s[38:39], 0, v[134:135]
	s_add_i32 m0, s47, 0xe000
	s_nop 0
	global_load_lds_dwordx4 v[144:145], off
	v_lshl_add_u64 v[238:239], s[44:45], 0, v[0:1]
	v_lshl_add_u64 v[240:241], s[44:45], 0, v[130:131]
	s_add_i32 m0, vcc_hi, s47
	s_nop 0
	global_load_lds_dwordx4 v[238:239], off
	s_add_i32 m0, m0, 0x2000
	s_nop 0
	global_load_lds_dwordx4 v[240:241], off
	s_waitcnt vmcnt(10)
	s_waitcnt lgkmcnt(0)
	s_setprio 1
	s_waitcnt lgkmcnt(0)
	v_mfma_f32_16x16x32_bf16 v[98:101], v[136:139], v[174:177], v[98:101]
	v_mfma_f32_16x16x32_bf16 v[34:37], v[150:153], v[174:177], v[34:37]
	v_mfma_f32_16x16x32_bf16 v[102:105], v[136:139], v[182:185], v[102:105]
	v_mfma_f32_16x16x32_bf16 v[42:45], v[150:153], v[182:185], v[42:45]
	s_barrier
	v_mfma_f32_16x16x32_bf16 v[106:109], v[136:139], v[190:193], v[106:109]
	v_mfma_f32_16x16x32_bf16 v[50:53], v[150:153], v[190:193], v[50:53]
	v_mfma_f32_16x16x32_bf16 v[110:113], v[136:139], v[206:209], v[110:113]
	v_mfma_f32_16x16x32_bf16 v[58:61], v[150:153], v[206:209], v[58:61]
	v_mfma_f32_16x16x32_bf16 v[98:101], v[140:143], v[178:181], v[98:101]
	v_mfma_f32_16x16x32_bf16 v[34:37], v[154:157], v[178:181], v[34:37]
	v_mfma_f32_16x16x32_bf16 v[102:105], v[140:143], v[186:189], v[102:105]
	v_mfma_f32_16x16x32_bf16 v[42:45], v[154:157], v[186:189], v[42:45]
	v_mfma_f32_16x16x32_bf16 v[106:109], v[140:143], v[202:205], v[106:109]
	v_mfma_f32_16x16x32_bf16 v[50:53], v[154:157], v[202:205], v[50:53]
	v_mfma_f32_16x16x32_bf16 v[110:113], v[140:143], v[210:213], v[110:113]
	v_mfma_f32_16x16x32_bf16 v[58:61], v[154:157], v[210:213], v[58:61]
	s_setprio 0
	s_setprio 1
	v_mfma_f32_16x16x32_bf16 v[38:41], v[158:161], v[174:177], v[38:41]
	v_mfma_f32_16x16x32_bf16 v[2:5], v[166:169], v[174:177], v[2:5]
	v_mfma_f32_16x16x32_bf16 v[46:49], v[158:161], v[182:185], v[46:49]
	v_mfma_f32_16x16x32_bf16 v[6:9], v[166:169], v[182:185], v[6:9]
	v_mfma_f32_16x16x32_bf16 v[54:57], v[158:161], v[190:193], v[54:57]
	v_mfma_f32_16x16x32_bf16 v[10:13], v[166:169], v[190:193], v[10:13]
	v_mfma_f32_16x16x32_bf16 v[62:65], v[158:161], v[206:209], v[62:65]
	v_mfma_f32_16x16x32_bf16 v[14:17], v[166:169], v[206:209], v[14:17]
	v_mfma_f32_16x16x32_bf16 v[38:41], v[162:165], v[178:181], v[38:41]
	v_mfma_f32_16x16x32_bf16 v[2:5], v[170:173], v[178:181], v[2:5]
	v_mfma_f32_16x16x32_bf16 v[46:49], v[162:165], v[186:189], v[46:49]
	v_mfma_f32_16x16x32_bf16 v[6:9], v[170:173], v[186:189], v[6:9]
	v_mfma_f32_16x16x32_bf16 v[54:57], v[162:165], v[202:205], v[54:57]
	v_mfma_f32_16x16x32_bf16 v[10:13], v[170:173], v[202:205], v[10:13]
	v_mfma_f32_16x16x32_bf16 v[62:65], v[162:165], v[210:213], v[62:65]
	v_mfma_f32_16x16x32_bf16 v[14:17], v[170:173], v[210:213], v[14:17]
	s_setprio 0
	s_barrier
	s_add_i32 s38, s65, s31
	v_lshl_add_u64 v[144:145], s[42:43], 0, v[0:1]
	s_mov_b32 m0, s38
	ds_read_b128 v[174:177], v149 offset:16384
	ds_read_b128 v[178:181], v149 offset:17408
	ds_read_b128 v[182:185], v149 offset:18432
	ds_read_b128 v[186:189], v149 offset:19456
	ds_read_b128 v[190:193], v149 offset:20480
	ds_read_b128 v[202:205], v149 offset:21504
	ds_read_b128 v[206:209], v149 offset:22528
	ds_read_b128 v[210:213], v149 offset:23552
	global_load_lds_dwordx4 v[144:145], off
	s_add_i32 m0, s38, 0x2000
	s_add_u32 s38, s42, 0x160000
	v_lshl_add_u64 v[194:195], s[42:43], 0, v[130:131]
	s_addc_u32 s39, s43, 0
	s_add_i32 s65, s66, s31
	global_load_lds_dwordx4 v[194:195], off
	v_lshl_add_u64 v[214:215], s[38:39], 0, v[0:1]
	s_mov_b32 m0, s65
	s_nop 0
	global_load_lds_dwordx4 v[214:215], off
	v_lshl_add_u64 v[214:215], s[38:39], 0, v[130:131]
	s_add_i32 m0, s65, 0x2000
	s_nop 0
	global_load_lds_dwordx4 v[214:215], off
	s_waitcnt vmcnt(8)
	s_waitcnt lgkmcnt(0)
	s_setprio 1
	s_waitcnt lgkmcnt(0)
	v_mfma_f32_16x16x32_bf16 v[114:117], v[136:139], v[174:177], v[114:117]
	v_mfma_f32_16x16x32_bf16 v[66:69], v[150:153], v[174:177], v[66:69]
	v_mfma_f32_16x16x32_bf16 v[118:121], v[136:139], v[182:185], v[118:121]
	v_mfma_f32_16x16x32_bf16 v[74:77], v[150:153], v[182:185], v[74:77]
	s_barrier
; #define PG8_STAGE(bufoff, gbase, voff) do { _Pragma("unroll") for (int _i = 0; _i < 2; ++_i) \
;         __builtin_amdgcn_global_load_lds((const unsigned*)((const char*)(gbase) + (voff)[_i]), (PG8_LAS unsigned*)(lds + (bufoff) + ldsw + _i * 8192), 16, 0, 0); } while (0)
; #define PG8_LDA(dst, b, h) do { _Pragma("unroll") for (int m = 0; m < 4; ++m) _Pragma("unroll") for (int k = 0; k < 2; ++k) dst[m][k] = *(const PG8_LAS bf16x8*)(lds + PG8_SA(b, h) + aoff + m * 2048 + k * 1024); } while (0)
; #define PG8_LDB(dst, b, h) do { _Pragma("unroll") for (int n = 0; n < 2; ++n) _Pragma("unroll") for (int k = 0; k < 2; ++k) dst[n][k] = *(const PG8_LAS bf16x8*)(lds + PG8_SB(b, h) + boff + n * 2048 + k * 1024); } while (0)
; template <class Epi, class Sched, bool ALIGN_EPI = false, bool SP2 = false>
; __device__ __forceinline__ void gemm_phase(PG8_LAS unsigned char* lds, const Gemm g, const Sched& S, const Epi& E) {
;     ...
;         for (int t = 0; t < nt; t += 2) {
;             const bool last = (t == nt - 2);
;             const char* a1 = cA + (size_t)(t + 1) * kstep;
;             const char* a2 = last ? nA : cA + (size_t)(t + 2) * kstep; const char* b2 = last ? nB : cB + (size_t)(t + 2) * kstep;
;             const char* a3 = a2 + kstep; const char* b3 = b2 + kstep;
;             if (last && has_next) S.a_ready(nxt);
;             if constexpr (SP2) {
;             PG8_LDB(B0, 0, 0); PG8_LDB(B1, 0, 1); PG8_SCHED; PG8_LDA(At, 0, 0); PG8_STAGE(PG8_SA(1, 1), a1 + hstep, voffA);
;             PG8_WAIT_V(8); PG8_WAIT_L(0); PG8_BAR; PG8_MMA(0, 0, At, B0); PG8_MMA(0, 1, At, B1); PG8_BAR; PG8_SCHED;
;             PG8_LDA(At, 0, 1); PG8_STAGE(PG8_SB(0, 0), b2, voffB); PG8_STAGE(PG8_SB(0, 1), b2 + hstep, voffB); PG8_STAGE(PG8_SA(0, 0), a2, voffA);
;             PG8_WAIT_V(8); PG8_WAIT_L(0); PG8_BAR; PG8_MMA(1, 0, At, B0); PG8_MMA(1, 1, At, B1); PG8_BAR; PG8_SCHED;
;             PG8_LDB(B0, 1, 0); PG8_LDB(B1, 1, 1); PG8_SCHED; PG8_LDA(At, 1, 0); PG8_STAGE(PG8_SA(0, 1), a2 + hstep, voffA);
;             PG8_WAIT_V(8); PG8_WAIT_L(0); PG8_BAR; PG8_MMA(0, 0, At, B0); PG8_MMA(0, 1, At, B1); PG8_BAR; PG8_SCHED;
;             PG8_LDA(At, 1, 1); PG8_STAGE(PG8_SB(1, 0), b3, voffB); PG8_STAGE(PG8_SB(1, 1), b3 + hstep, voffB); PG8_STAGE(PG8_SA(1, 0), a3, voffA);
;             PG8_WAIT_V(8); PG8_WAIT_L(0); PG8_BAR; PG8_MMA(1, 0, At, B0); PG8_MMA(1, 1, At, B1); PG8_BAR; PG8_SCHED;
	v_mfma_f32_16x16x32_bf16 v[122:125], v[136:139], v[190:193], v[122:125]
	v_mfma_f32_16x16x32_bf16 v[82:85], v[150:153], v[190:193], v[82:85]
	v_mfma_f32_16x16x32_bf16 v[126:129], v[136:139], v[206:209], v[126:129]
	v_mfma_f32_16x16x32_bf16 v[90:93], v[150:153], v[206:209], v[90:93]
	v_mfma_f32_16x16x32_bf16 v[114:117], v[140:143], v[178:181], v[114:117]
	v_mfma_f32_16x16x32_bf16 v[66:69], v[154:157], v[178:181], v[66:69]
	v_mfma_f32_16x16x32_bf16 v[118:121], v[140:143], v[186:189], v[118:121]
	v_mfma_f32_16x16x32_bf16 v[74:77], v[154:157], v[186:189], v[74:77]
	v_mfma_f32_16x16x32_bf16 v[122:125], v[140:143], v[202:205], v[122:125]
	v_mfma_f32_16x16x32_bf16 v[82:85], v[154:157], v[202:205], v[82:85]
	v_mfma_f32_16x16x32_bf16 v[126:129], v[140:143], v[210:213], v[126:129]
	v_mfma_f32_16x16x32_bf16 v[90:93], v[154:157], v[210:213], v[90:93]
	s_setprio 0
	s_setprio 1
	v_mfma_f32_16x16x32_bf16 v[70:73], v[158:161], v[174:177], v[70:73]
	v_mfma_f32_16x16x32_bf16 v[18:21], v[166:169], v[174:177], v[18:21]
	v_mfma_f32_16x16x32_bf16 v[78:81], v[158:161], v[182:185], v[78:81]
	v_mfma_f32_16x16x32_bf16 v[22:25], v[166:169], v[182:185], v[22:25]
	v_mfma_f32_16x16x32_bf16 v[86:89], v[158:161], v[190:193], v[86:89]
	v_mfma_f32_16x16x32_bf16 v[26:29], v[166:169], v[190:193], v[26:29]
	v_mfma_f32_16x16x32_bf16 v[94:97], v[158:161], v[206:209], v[94:97]
	v_mfma_f32_16x16x32_bf16 v[30:33], v[166:169], v[206:209], v[30:33]
	v_mfma_f32_16x16x32_bf16 v[70:73], v[162:165], v[178:181], v[70:73]
	v_mfma_f32_16x16x32_bf16 v[18:21], v[170:173], v[178:181], v[18:21]
	v_mfma_f32_16x16x32_bf16 v[78:81], v[162:165], v[186:189], v[78:81]
	v_mfma_f32_16x16x32_bf16 v[22:25], v[170:173], v[186:189], v[22:25]
	v_mfma_f32_16x16x32_bf16 v[86:89], v[162:165], v[202:205], v[86:89]
	v_mfma_f32_16x16x32_bf16 v[26:29], v[170:173], v[202:205], v[26:29]
	v_mfma_f32_16x16x32_bf16 v[94:97], v[162:165], v[210:213], v[94:97]
	v_mfma_f32_16x16x32_bf16 v[30:33], v[170:173], v[210:213], v[30:33]
	s_setprio 0
	s_barrier
	s_add_i32 s65, 0, 0x18000
	s_add_i32 s66, 0, 0x1c000
	v_add_u32_e32 v154, s65, v147
	v_add_u32_e32 v170, s66, v147
	ds_read_b128 v[136:139], v154
	ds_read_b128 v[140:143], v154 offset:1024
	ds_read_b128 v[150:153], v154 offset:2048
	ds_read_b128 v[154:157], v154 offset:3072
	ds_read_b128 v[158:161], v170
	ds_read_b128 v[162:165], v170 offset:1024
	ds_read_b128 v[166:169], v170 offset:2048
	ds_read_b128 v[170:173], v170 offset:3072
	s_add_u32 s38, s44, 0x160000
	s_addc_u32 s39, s45, 0
	s_mov_b32 m0, s49
	v_lshl_add_u64 v[218:219], s[38:39], 0, v[0:1]
	v_add_u32_e32 v250, s101, v149
	ds_read_b128 v[174:177], v250
	ds_read_b128 v[178:181], v250 offset:1024
	ds_read_b128 v[182:185], v250 offset:2048
	ds_read_b128 v[186:189], v250 offset:3072
	ds_read_b128 v[190:193], v250 offset:4096
	ds_read_b128 v[202:205], v250 offset:5120
	ds_read_b128 v[206:209], v250 offset:6144
	ds_read_b128 v[210:213], v250 offset:7168
	global_load_lds_dwordx4 v[218:219], off
	v_lshl_add_u64 v[218:219], s[38:39], 0, v[130:131]
	s_mov_b32 m0, s50
	s_nop 0
	global_load_lds_dwordx4 v[218:219], off
	v_lshl_add_u64 v[242:243], v[238:239], 0, s[96:97]
	v_lshl_add_u64 v[244:245], v[240:241], 0, s[96:97]
	s_add_i32 m0, s100, s47
	s_nop 0
	global_load_lds_dwordx4 v[242:243], off
	s_add_i32 m0, m0, 0x2000
	s_nop 0
	global_load_lds_dwordx4 v[244:245], off
	s_waitcnt vmcnt(10)
	s_waitcnt lgkmcnt(0)
	s_setprio 1
	s_waitcnt lgkmcnt(0)
	v_mfma_f32_16x16x32_bf16 v[98:101], v[136:139], v[174:177], v[98:101]
	v_mfma_f32_16x16x32_bf16 v[34:37], v[150:153], v[174:177], v[34:37]
	v_mfma_f32_16x16x32_bf16 v[102:105], v[136:139], v[182:185], v[102:105]
	v_mfma_f32_16x16x32_bf16 v[42:45], v[150:153], v[182:185], v[42:45]
	s_barrier
; #define PG8_STAGE(bufoff, gbase, voff) do { _Pragma("unroll") for (int _i = 0; _i < 2; ++_i) \
;         __builtin_amdgcn_global_load_lds((const unsigned*)((const char*)(gbase) + (voff)[_i]), (PG8_LAS unsigned*)(lds + (bufoff) + ldsw + _i * 8192), 16, 0, 0); } while (0)
; #define PG8_LDA(dst, b, h) do { _Pragma("unroll") for (int m = 0; m < 4; ++m) _Pragma("unroll") for (int k = 0; k < 2; ++k) dst[m][k] = *(const PG8_LAS bf16x8*)(lds + PG8_SA(b, h) + aoff + m * 2048 + k * 1024); } while (0)
; #define PG8_LDB(dst, b, h) do { _Pragma("unroll") for (int n = 0; n < 2; ++n) _Pragma("unroll") for (int k = 0; k < 2; ++k) dst[n][k] = *(const PG8_LAS bf16x8*)(lds + PG8_SB(b, h) + boff + n * 2048 + k * 1024); } while (0)
; template <class Epi, class Sched, bool ALIGN_EPI = false, bool SP2 = false>
; __device__ __forceinline__ void gemm_phase(PG8_LAS unsigned char* lds, const Gemm g, const Sched& S, const Epi& E) {
;     ...
;         for (int t = 0; t < nt; t += 2) {
;             const bool last = (t == nt - 2);
;             const char* a1 = cA + (size_t)(t + 1) * kstep;
;             const char* a2 = last ? nA : cA + (size_t)(t + 2) * kstep; const char* b2 = last ? nB : cB + (size_t)(t + 2) * kstep;
;             const char* a3 = a2 + kstep; const char* b3 = b2 + kstep;
;             if (last && has_next) S.a_ready(nxt);
;             if constexpr (SP2) {
;             PG8_LDB(B0, 0, 0); PG8_LDB(B1, 0, 1); PG8_SCHED; PG8_LDA(At, 0, 0); PG8_STAGE(PG8_SA(1, 1), a1 + hstep, voffA);
;             PG8_WAIT_V(8); PG8_WAIT_L(0); PG8_BAR; PG8_MMA(0, 0, At, B0); PG8_MMA(0, 1, At, B1); PG8_BAR; PG8_SCHED;
;             PG8_LDA(At, 0, 1); PG8_STAGE(PG8_SB(0, 0), b2, voffB); PG8_STAGE(PG8_SB(0, 1), b2 + hstep, voffB); PG8_STAGE(PG8_SA(0, 0), a2, voffA);
;             PG8_WAIT_V(8); PG8_WAIT_L(0); PG8_BAR; PG8_MMA(1, 0, At, B0); PG8_MMA(1, 1, At, B1); PG8_BAR; PG8_SCHED;
;             PG8_LDB(B0, 1, 0); PG8_LDB(B1, 1, 1); PG8_SCHED; PG8_LDA(At, 1, 0); PG8_STAGE(PG8_SA(0, 1), a2 + hstep, voffA);
;             PG8_WAIT_V(8); PG8_WAIT_L(0); PG8_BAR; PG8_MMA(0, 0, At, B0); PG8_MMA(0, 1, At, B1); PG8_BAR; PG8_SCHED;
;             PG8_LDA(At, 1, 1); PG8_STAGE(PG8_SB(1, 0), b3, voffB); PG8_STAGE(PG8_SB(1, 1), b3 + hstep, voffB); PG8_STAGE(PG8_SA(1, 0), a3, voffA);
;             PG8_WAIT_V(8); PG8_WAIT_L(0); PG8_BAR; PG8_MMA(1, 0, At, B0); PG8_MMA(1, 1, At, B1); PG8_BAR; PG8_SCHED;
	v_mfma_f32_16x16x32_bf16 v[106:109], v[136:139], v[190:193], v[106:109]
	v_mfma_f32_16x16x32_bf16 v[50:53], v[150:153], v[190:193], v[50:53]
	v_mfma_f32_16x16x32_bf16 v[110:113], v[136:139], v[206:209], v[110:113]
	v_mfma_f32_16x16x32_bf16 v[58:61], v[150:153], v[206:209], v[58:61]
	v_mfma_f32_16x16x32_bf16 v[98:101], v[140:143], v[178:181], v[98:101]
	v_mfma_f32_16x16x32_bf16 v[34:37], v[154:157], v[178:181], v[34:37]
	v_mfma_f32_16x16x32_bf16 v[102:105], v[140:143], v[186:189], v[102:105]
	v_mfma_f32_16x16x32_bf16 v[42:45], v[154:157], v[186:189], v[42:45]
	v_mfma_f32_16x16x32_bf16 v[106:109], v[140:143], v[202:205], v[106:109]
	v_mfma_f32_16x16x32_bf16 v[50:53], v[154:157], v[202:205], v[50:53]
	v_mfma_f32_16x16x32_bf16 v[110:113], v[140:143], v[210:213], v[110:113]
	v_mfma_f32_16x16x32_bf16 v[58:61], v[154:157], v[210:213], v[58:61]
	s_setprio 0
	s_setprio 1
	v_mfma_f32_16x16x32_bf16 v[38:41], v[158:161], v[174:177], v[38:41]
	v_mfma_f32_16x16x32_bf16 v[2:5], v[166:169], v[174:177], v[2:5]
	v_mfma_f32_16x16x32_bf16 v[46:49], v[158:161], v[182:185], v[46:49]
	v_mfma_f32_16x16x32_bf16 v[6:9], v[166:169], v[182:185], v[6:9]
	v_mfma_f32_16x16x32_bf16 v[54:57], v[158:161], v[190:193], v[54:57]
	v_mfma_f32_16x16x32_bf16 v[10:13], v[166:169], v[190:193], v[10:13]
	v_mfma_f32_16x16x32_bf16 v[62:65], v[158:161], v[206:209], v[62:65]
	v_mfma_f32_16x16x32_bf16 v[14:17], v[166:169], v[206:209], v[14:17]
	v_mfma_f32_16x16x32_bf16 v[38:41], v[162:165], v[178:181], v[38:41]
	v_mfma_f32_16x16x32_bf16 v[2:5], v[170:173], v[178:181], v[2:5]
	v_mfma_f32_16x16x32_bf16 v[46:49], v[162:165], v[186:189], v[46:49]
	v_mfma_f32_16x16x32_bf16 v[6:9], v[170:173], v[186:189], v[6:9]
	v_mfma_f32_16x16x32_bf16 v[54:57], v[162:165], v[202:205], v[54:57]
	v_mfma_f32_16x16x32_bf16 v[10:13], v[170:173], v[202:205], v[10:13]
	v_mfma_f32_16x16x32_bf16 v[62:65], v[162:165], v[210:213], v[62:65]
	v_mfma_f32_16x16x32_bf16 v[14:17], v[170:173], v[210:213], v[14:17]
	s_setprio 0
	s_barrier
	s_add_i32 s38, s65, s31
	v_lshl_add_u64 v[144:145], v[144:145], 0, s[96:97]
	s_mov_b32 m0, s38
	ds_read_b128 v[174:177], v149 offset:49152
	ds_read_b128 v[178:181], v149 offset:50176
	ds_read_b128 v[182:185], v149 offset:51200
	ds_read_b128 v[186:189], v149 offset:52224
	ds_read_b128 v[190:193], v149 offset:53248
	ds_read_b128 v[202:205], v149 offset:54272
	ds_read_b128 v[206:209], v149 offset:55296
	ds_read_b128 v[210:213], v149 offset:56320
	global_load_lds_dwordx4 v[144:145], off
	s_add_i32 m0, s38, 0x2000
	s_add_u32 s38, s42, 0x160080
	v_lshl_add_u64 v[144:145], v[194:195], 0, s[96:97]
	s_addc_u32 s39, s43, 0
	s_add_i32 s42, s66, s31
	global_load_lds_dwordx4 v[144:145], off
	v_lshl_add_u64 v[144:145], s[38:39], 0, v[0:1]
	s_mov_b32 m0, s42
	s_nop 0
	global_load_lds_dwordx4 v[144:145], off
	v_lshl_add_u64 v[144:145], s[38:39], 0, v[130:131]
	s_add_i32 m0, s42, 0x2000
	s_nop 0
	global_load_lds_dwordx4 v[144:145], off
	s_waitcnt vmcnt(8)
	s_waitcnt lgkmcnt(0)
	s_setprio 1
	s_waitcnt lgkmcnt(0)
	v_mfma_f32_16x16x32_bf16 v[114:117], v[136:139], v[174:177], v[114:117]
	v_mfma_f32_16x16x32_bf16 v[66:69], v[150:153], v[174:177], v[66:69]
	v_mfma_f32_16x16x32_bf16 v[118:121], v[136:139], v[182:185], v[118:121]
	v_mfma_f32_16x16x32_bf16 v[74:77], v[150:153], v[182:185], v[74:77]
	s_barrier
	v_mfma_f32_16x16x32_bf16 v[122:125], v[136:139], v[190:193], v[122:125]
	v_mfma_f32_16x16x32_bf16 v[82:85], v[150:153], v[190:193], v[82:85]
	v_mfma_f32_16x16x32_bf16 v[126:129], v[136:139], v[206:209], v[126:129]
	v_mfma_f32_16x16x32_bf16 v[90:93], v[150:153], v[206:209], v[90:93]
	v_mfma_f32_16x16x32_bf16 v[114:117], v[140:143], v[178:181], v[114:117]
	v_mfma_f32_16x16x32_bf16 v[66:69], v[154:157], v[178:181], v[66:69]
	v_mfma_f32_16x16x32_bf16 v[118:121], v[140:143], v[186:189], v[118:121]
	v_mfma_f32_16x16x32_bf16 v[74:77], v[154:157], v[186:189], v[74:77]
	v_mfma_f32_16x16x32_bf16 v[122:125], v[140:143], v[202:205], v[122:125]
	v_mfma_f32_16x16x32_bf16 v[82:85], v[154:157], v[202:205], v[82:85]
	v_mfma_f32_16x16x32_bf16 v[126:129], v[140:143], v[210:213], v[126:129]
	v_mfma_f32_16x16x32_bf16 v[90:93], v[154:157], v[210:213], v[90:93]
	s_setprio 0
	s_setprio 1
	v_mfma_f32_16x16x32_bf16 v[70:73], v[158:161], v[174:177], v[70:73]
	v_mfma_f32_16x16x32_bf16 v[18:21], v[166:169], v[174:177], v[18:21]
	v_mfma_f32_16x16x32_bf16 v[78:81], v[158:161], v[182:185], v[78:81]
	v_mfma_f32_16x16x32_bf16 v[22:25], v[166:169], v[182:185], v[22:25]
	v_mfma_f32_16x16x32_bf16 v[86:89], v[158:161], v[190:193], v[86:89]
	v_mfma_f32_16x16x32_bf16 v[26:29], v[166:169], v[190:193], v[26:29]
	v_mfma_f32_16x16x32_bf16 v[94:97], v[158:161], v[206:209], v[94:97]
	v_mfma_f32_16x16x32_bf16 v[30:33], v[166:169], v[206:209], v[30:33]
	v_mfma_f32_16x16x32_bf16 v[70:73], v[162:165], v[178:181], v[70:73]
	v_mfma_f32_16x16x32_bf16 v[18:21], v[170:173], v[178:181], v[18:21]
	v_mfma_f32_16x16x32_bf16 v[78:81], v[162:165], v[186:189], v[78:81]
	v_mfma_f32_16x16x32_bf16 v[22:25], v[170:173], v[186:189], v[22:25]
	v_mfma_f32_16x16x32_bf16 v[86:89], v[162:165], v[202:205], v[86:89]
	v_mfma_f32_16x16x32_bf16 v[26:29], v[170:173], v[202:205], v[26:29]
	v_mfma_f32_16x16x32_bf16 v[94:97], v[162:165], v[210:213], v[94:97]
	v_mfma_f32_16x16x32_bf16 v[30:33], v[170:173], v[210:213], v[30:33]
	s_setprio 0
	s_barrier
	s_add_i32 s64, s64, 2
	s_mov_b32 s101, s100
	s_mov_b32 s100, vcc_hi
	s_add_u32 s62, s62, 0x100
	s_addc_u32 s63, s63, 0
	s_cmpk_gt_u32 s64, 0x55
	s_mov_b64 s[38:39], s[40:41]
	s_cbranch_scc0 .LBB0_1593
	s_and_b64 vcc, exec, s[24:25]
	s_cbranch_vccz .LBB0_1596
	s_barrier
